# merge GEMM: aligned gate hooks (leading group waits before the hook, lagging group re-staggers after it) on top of the late stagger barrier
# baseline (speedup 1.0000x reference)
.LBB0_1008:
	s_andn2_b64 vcc, exec, s[28:29]
	s_cbranch_vccnz .LBB0_1003
	s_and_b64 vcc, exec, s[16:17]
	s_cbranch_vccz .Lhk_a_1
	s_barrier
.Lhk_a_1:
	v_mov_b32_e32 v129, v192
	v_mov_b32_e32 v128, v193
	s_and_b32 s6, s26, 0xc00
	v_add_u32_e32 v198, s59, v129
	v_mov_b64_e32 v[188:189], s[10:11]
	v_lshl_add_u32 v128, v128, 3, s58
	s_addk_i32 s6, 0xfc00
	v_mad_i64_i32 v[130:131], s[28:29], v198, s49, v[188:189]
	v_ashrrev_i32_e32 v129, 31, v128
	s_lshl_b64 s[28:29], s[6:7], 1
	v_lshl_add_u64 v[130:131], v[130:131], 0, s[28:29]
	v_lshlrev_b64 v[190:191], 1, v[128:129]
	v_lshl_add_u64 v[128:129], v[130:131], 0, v[190:191]
	v_lshl_add_u64 v[130:131], v[128:129], 0, s[18:19]
	global_load_dwordx4 v[200:203], v[128:129], off offset:3584
	global_load_dwordx4 v[206:209], v[128:129], off offset:3840
	global_load_dwordx4 v[210:213], v[130:131], off offset:2048
	global_load_dwordx4 v[214:217], v[130:131], off offset:2304
	v_add_u32_e32 v128, 16, v198
	v_mad_i64_i32 v[128:129], s[30:31], v128, s49, v[188:189]
	v_lshl_add_u64 v[128:129], v[128:129], 0, s[28:29]
	v_lshl_add_u64 v[128:129], v[128:129], 0, v[190:191]
	v_lshl_add_u64 v[130:131], v[128:129], 0, s[18:19]
	global_load_dwordx4 v[218:221], v[128:129], off offset:3584
	global_load_dwordx4 v[160:163], v[128:129], off offset:3840
	global_load_dwordx4 v[222:225], v[130:131], off offset:2048
	global_load_dwordx4 v[164:167], v[130:131], off offset:2304
	v_add_u32_e32 v128, 32, v198
	v_mad_i64_i32 v[128:129], s[30:31], v128, s49, v[188:189]
	v_lshl_add_u64 v[128:129], v[128:129], 0, s[28:29]
	v_lshl_add_u64 v[128:129], v[128:129], 0, v[190:191]
	v_lshl_add_u64 v[130:131], v[128:129], 0, s[18:19]
	global_load_dwordx4 v[152:155], v[128:129], off offset:3584
	global_load_dwordx4 v[144:147], v[128:129], off offset:3840
	global_load_dwordx4 v[156:159], v[130:131], off offset:2048
	global_load_dwordx4 v[148:151], v[130:131], off offset:2304
	v_add_u32_e32 v128, 48, v198
	v_mad_i64_i32 v[128:129], s[30:31], v128, s49, v[188:189]
	v_lshl_add_u64 v[128:129], v[128:129], 0, s[28:29]
	v_lshl_add_u64 v[128:129], v[128:129], 0, v[190:191]
	v_lshl_add_u64 v[132:133], v[128:129], 0, s[18:19]
	global_load_dwordx4 v[136:139], v[128:129], off offset:3584
	s_nop 0
	global_load_dwordx4 v[128:131], v[128:129], off offset:3840
	s_nop 0
	global_load_dwordx4 v[140:143], v[132:133], off offset:2048
	s_nop 0
	global_load_dwordx4 v[132:135], v[132:133], off offset:2304
	s_waitcnt vmcnt(0)
	v_lshlrev_b32_e32 v199, 16, v210
	v_max_f32_e32 v199, v199, v199
	v_max_f32_e32 v199, 0x1e3ce508, v199
	v_rcp_f32_e32 v226, v199
	v_and_b32_e32 v199, 0xffff0000, v210
	v_max_f32_e32 v199, v199, v199
	v_max_f32_e32 v199, 0x1e3ce508, v199
	v_rcp_f32_e32 v227, v199
	v_lshlrev_b32_e32 v199, 16, v211
	v_max_f32_e32 v199, v199, v199
	v_max_f32_e32 v199, 0x1e3ce508, v199
	v_rcp_f32_e32 v210, v199
	v_and_b32_e32 v199, 0xffff0000, v211
	v_max_f32_e32 v199, v199, v199
	v_max_f32_e32 v199, 0x1e3ce508, v199
	v_rcp_f32_e32 v211, v199
	v_lshlrev_b32_e32 v199, 16, v212
	v_max_f32_e32 v199, v199, v199
	v_lshlrev_b32_e32 v228, 16, v200
	v_and_b32_e32 v229, 0xffff0000, v200
	v_lshlrev_b32_e32 v200, 16, v201
	v_and_b32_e32 v201, 0xffff0000, v201
	v_max_f32_e32 v199, 0x1e3ce508, v199
	v_pk_mul_f32 v[200:201], v[210:211], v[200:201]
	v_rcp_f32_e32 v210, v199
	v_and_b32_e32 v199, 0xffff0000, v212
	v_max_f32_e32 v199, v199, v199
	v_max_f32_e32 v199, 0x1e3ce508, v199
	v_rcp_f32_e32 v211, v199
	v_lshlrev_b32_e32 v199, 16, v213
	v_max_f32_e32 v199, v199, v199
	v_pk_mul_f32 v[126:127], v[126:127], v[200:201]
	v_lshlrev_b32_e32 v200, 16, v202
	v_and_b32_e32 v201, 0xffff0000, v202
	v_max_f32_e32 v199, 0x1e3ce508, v199
	v_pk_mul_f32 v[200:201], v[210:211], v[200:201]
	v_rcp_f32_e32 v210, v199
	v_and_b32_e32 v199, 0xffff0000, v213
	v_max_f32_e32 v199, v199, v199
	v_max_f32_e32 v199, 0x1e3ce508, v199
	v_rcp_f32_e32 v211, v199
	v_lshlrev_b32_e32 v199, 16, v214
	v_max_f32_e32 v199, v199, v199
	v_max_f32_e32 v199, 0x1e3ce508, v199
	v_rcp_f32_e32 v202, v199
	v_and_b32_e32 v199, 0xffff0000, v214
	v_max_f32_e32 v199, v199, v199
	v_max_f32_e32 v199, 0x1e3ce508, v199
	v_pk_mul_f32 v[120:121], v[120:121], v[200:201]
	v_lshlrev_b32_e32 v200, 16, v203
	v_and_b32_e32 v201, 0xffff0000, v203
	v_rcp_f32_e32 v203, v199
	v_lshlrev_b32_e32 v199, 16, v215
	v_pk_mul_f32 v[200:201], v[210:211], v[200:201]
	v_max_f32_e32 v199, v199, v199
	v_pk_mul_f32 v[122:123], v[122:123], v[200:201]
	v_lshlrev_b32_e32 v200, 16, v206
	v_and_b32_e32 v201, 0xffff0000, v206
	v_max_f32_e32 v199, 0x1e3ce508, v199
	v_pk_mul_f32 v[200:201], v[202:203], v[200:201]
	v_rcp_f32_e32 v202, v199
	v_and_b32_e32 v199, 0xffff0000, v215
	v_max_f32_e32 v199, v199, v199
	v_max_f32_e32 v199, 0x1e3ce508, v199
	v_rcp_f32_e32 v203, v199
	v_lshlrev_b32_e32 v199, 16, v216
	v_max_f32_e32 v199, v199, v199
	v_pk_mul_f32 v[116:117], v[116:117], v[200:201]
	v_lshlrev_b32_e32 v200, 16, v207
	v_and_b32_e32 v201, 0xffff0000, v207
	v_max_f32_e32 v199, 0x1e3ce508, v199
	v_pk_mul_f32 v[200:201], v[202:203], v[200:201]
	v_rcp_f32_e32 v202, v199
	v_and_b32_e32 v199, 0xffff0000, v216
	v_max_f32_e32 v199, v199, v199
	v_max_f32_e32 v199, 0x1e3ce508, v199
	v_rcp_f32_e32 v203, v199
	v_lshlrev_b32_e32 v199, 16, v217
	v_max_f32_e32 v199, v199, v199
	v_pk_mul_f32 v[118:119], v[118:119], v[200:201]
	v_lshlrev_b32_e32 v200, 16, v208
	v_and_b32_e32 v201, 0xffff0000, v208
	v_max_f32_e32 v199, 0x1e3ce508, v199
	v_pk_mul_f32 v[200:201], v[202:203], v[200:201]
	v_rcp_f32_e32 v202, v199
	v_and_b32_e32 v199, 0xffff0000, v217
	v_max_f32_e32 v199, v199, v199
	v_max_f32_e32 v199, 0x1e3ce508, v199
	v_rcp_f32_e32 v203, v199
	v_lshlrev_b32_e32 v199, 16, v222
	v_max_f32_e32 v199, v199, v199
	v_pk_mul_f32 v[112:113], v[112:113], v[200:201]
	v_lshlrev_b32_e32 v200, 16, v209
	v_and_b32_e32 v201, 0xffff0000, v209
	v_max_f32_e32 v199, 0x1e3ce508, v199
	v_pk_mul_f32 v[200:201], v[202:203], v[200:201]
	v_rcp_f32_e32 v202, v199
	v_and_b32_e32 v199, 0xffff0000, v222
	v_max_f32_e32 v199, v199, v199
	v_max_f32_e32 v199, 0x1e3ce508, v199
	v_rcp_f32_e32 v203, v199
	v_lshlrev_b32_e32 v199, 16, v223
	v_max_f32_e32 v199, v199, v199
	v_pk_mul_f32 v[114:115], v[114:115], v[200:201]
	v_lshlrev_b32_e32 v200, 16, v218
	v_and_b32_e32 v201, 0xffff0000, v218
	v_max_f32_e32 v199, 0x1e3ce508, v199
	v_pk_mul_f32 v[200:201], v[202:203], v[200:201]
	v_rcp_f32_e32 v202, v199
	v_and_b32_e32 v199, 0xffff0000, v223
	v_max_f32_e32 v199, v199, v199
	v_max_f32_e32 v199, 0x1e3ce508, v199
	v_rcp_f32_e32 v203, v199
	v_lshlrev_b32_e32 v199, 16, v224
	v_max_f32_e32 v199, v199, v199
	v_pk_mul_f32 v[108:109], v[108:109], v[200:201]
	v_lshlrev_b32_e32 v200, 16, v219
	v_and_b32_e32 v201, 0xffff0000, v219
	v_max_f32_e32 v199, 0x1e3ce508, v199
	v_pk_mul_f32 v[200:201], v[202:203], v[200:201]
	v_rcp_f32_e32 v202, v199
	v_and_b32_e32 v199, 0xffff0000, v224
	v_max_f32_e32 v199, v199, v199
	v_max_f32_e32 v199, 0x1e3ce508, v199
	v_rcp_f32_e32 v203, v199
	v_lshlrev_b32_e32 v199, 16, v225
	v_max_f32_e32 v199, v199, v199
	v_pk_mul_f32 v[110:111], v[110:111], v[200:201]
	v_lshlrev_b32_e32 v200, 16, v220
	v_and_b32_e32 v201, 0xffff0000, v220
	v_max_f32_e32 v199, 0x1e3ce508, v199
	v_pk_mul_f32 v[200:201], v[202:203], v[200:201]
	v_rcp_f32_e32 v202, v199
	v_and_b32_e32 v199, 0xffff0000, v225
	v_max_f32_e32 v199, v199, v199
	v_max_f32_e32 v199, 0x1e3ce508, v199
	v_rcp_f32_e32 v203, v199
	v_pk_mul_f32 v[104:105], v[104:105], v[200:201]
	v_lshlrev_b32_e32 v200, 16, v221
	v_and_b32_e32 v201, 0xffff0000, v221
	v_pk_mul_f32 v[200:201], v[202:203], v[200:201]
	v_lshlrev_b32_e32 v199, 16, v164
	v_and_b32_e32 v164, 0xffff0000, v164
	v_pk_mul_f32 v[106:107], v[106:107], v[200:201]
	v_lshlrev_b32_e32 v200, 16, v160
	v_and_b32_e32 v201, 0xffff0000, v160
	v_lshlrev_b32_e32 v160, 16, v165
	v_max_f32_e32 v164, v164, v164
	v_max_f32_e32 v160, v160, v160
	v_max_f32_e32 v164, 0x1e3ce508, v164
	v_max_f32_e32 v160, 0x1e3ce508, v160
	v_rcp_f32_e32 v203, v164
	v_rcp_f32_e32 v164, v160
	v_and_b32_e32 v160, 0xffff0000, v165
	v_max_f32_e32 v160, v160, v160
	v_max_f32_e32 v160, 0x1e3ce508, v160
	v_rcp_f32_e32 v165, v160
	v_lshlrev_b32_e32 v160, 16, v161
	v_and_b32_e32 v161, 0xffff0000, v161
	v_max_f32_e32 v199, v199, v199
	v_pk_mul_f32 v[160:161], v[164:165], v[160:161]
	v_lshlrev_b32_e32 v164, 16, v166
	v_and_b32_e32 v165, 0xffff0000, v166
	v_max_f32_e32 v164, v164, v164
	v_max_f32_e32 v165, v165, v165
	v_max_f32_e32 v164, 0x1e3ce508, v164
	v_max_f32_e32 v165, 0x1e3ce508, v165
	v_rcp_f32_e32 v164, v164
	v_rcp_f32_e32 v165, v165
	v_pk_mul_f32 v[102:103], v[102:103], v[160:161]
	v_lshlrev_b32_e32 v160, 16, v162
	v_and_b32_e32 v161, 0xffff0000, v162
	v_lshlrev_b32_e32 v162, 16, v167
	v_max_f32_e32 v162, v162, v162
	v_max_f32_e32 v162, 0x1e3ce508, v162
	v_pk_mul_f32 v[160:161], v[164:165], v[160:161]
	v_rcp_f32_e32 v164, v162
	v_and_b32_e32 v162, 0xffff0000, v167
	v_max_f32_e32 v162, v162, v162
	v_max_f32_e32 v162, 0x1e3ce508, v162
	v_rcp_f32_e32 v165, v162
	v_pk_mul_f32 v[96:97], v[96:97], v[160:161]
	v_lshlrev_b32_e32 v160, 16, v163
	v_and_b32_e32 v161, 0xffff0000, v163
	v_pk_mul_f32 v[160:161], v[164:165], v[160:161]
	v_lshlrev_b32_e32 v162, 16, v156
	v_and_b32_e32 v156, 0xffff0000, v156
	v_pk_mul_f32 v[98:99], v[98:99], v[160:161]
	v_lshlrev_b32_e32 v160, 16, v152
	v_and_b32_e32 v161, 0xffff0000, v152
	v_lshlrev_b32_e32 v152, 16, v157
	v_max_f32_e32 v156, v156, v156
	v_max_f32_e32 v152, v152, v152
	v_max_f32_e32 v156, 0x1e3ce508, v156
	v_max_f32_e32 v152, 0x1e3ce508, v152
	v_rcp_f32_e32 v163, v156
	v_rcp_f32_e32 v156, v152
	v_and_b32_e32 v152, 0xffff0000, v157
	v_max_f32_e32 v152, v152, v152
	v_max_f32_e32 v152, 0x1e3ce508, v152
	v_rcp_f32_e32 v157, v152
	v_lshlrev_b32_e32 v152, 16, v153
	v_and_b32_e32 v153, 0xffff0000, v153
	v_max_f32_e32 v162, v162, v162
	v_pk_mul_f32 v[152:153], v[156:157], v[152:153]
	v_lshlrev_b32_e32 v156, 16, v158
	v_and_b32_e32 v157, 0xffff0000, v158
	v_max_f32_e32 v156, v156, v156
	v_max_f32_e32 v157, v157, v157
	v_max_f32_e32 v156, 0x1e3ce508, v156
	v_max_f32_e32 v157, 0x1e3ce508, v157
	v_rcp_f32_e32 v156, v156
	v_rcp_f32_e32 v157, v157
	v_pk_mul_f32 v[94:95], v[94:95], v[152:153]
	v_lshlrev_b32_e32 v152, 16, v154
	v_and_b32_e32 v153, 0xffff0000, v154
	v_lshlrev_b32_e32 v154, 16, v159
	v_max_f32_e32 v154, v154, v154
	v_max_f32_e32 v154, 0x1e3ce508, v154
	v_pk_mul_f32 v[152:153], v[156:157], v[152:153]
	v_rcp_f32_e32 v156, v154
	v_and_b32_e32 v154, 0xffff0000, v159
	v_max_f32_e32 v154, v154, v154
	v_max_f32_e32 v154, 0x1e3ce508, v154
	v_rcp_f32_e32 v157, v154
	v_pk_mul_f32 v[88:89], v[88:89], v[152:153]
	v_lshlrev_b32_e32 v152, 16, v155
	v_and_b32_e32 v153, 0xffff0000, v155
	v_pk_mul_f32 v[152:153], v[156:157], v[152:153]
	v_lshlrev_b32_e32 v154, 16, v148
	v_and_b32_e32 v148, 0xffff0000, v148
	v_pk_mul_f32 v[90:91], v[90:91], v[152:153]
	v_lshlrev_b32_e32 v152, 16, v144
	v_and_b32_e32 v153, 0xffff0000, v144
	v_lshlrev_b32_e32 v144, 16, v149
	v_max_f32_e32 v148, v148, v148
	v_max_f32_e32 v144, v144, v144
	v_max_f32_e32 v148, 0x1e3ce508, v148
	v_max_f32_e32 v144, 0x1e3ce508, v144
	v_rcp_f32_e32 v155, v148
	v_rcp_f32_e32 v148, v144
	v_and_b32_e32 v144, 0xffff0000, v149
	v_max_f32_e32 v144, v144, v144
	v_max_f32_e32 v144, 0x1e3ce508, v144
	v_rcp_f32_e32 v149, v144
	v_lshlrev_b32_e32 v144, 16, v145
	v_and_b32_e32 v145, 0xffff0000, v145
	v_max_f32_e32 v154, v154, v154
	v_pk_mul_f32 v[144:145], v[148:149], v[144:145]
	v_lshlrev_b32_e32 v148, 16, v150
	v_and_b32_e32 v149, 0xffff0000, v150
	v_max_f32_e32 v148, v148, v148
	v_max_f32_e32 v149, v149, v149
	v_max_f32_e32 v148, 0x1e3ce508, v148
	v_max_f32_e32 v149, 0x1e3ce508, v149
	v_rcp_f32_e32 v148, v148
	v_rcp_f32_e32 v149, v149
	v_pk_mul_f32 v[86:87], v[86:87], v[144:145]
	v_lshlrev_b32_e32 v144, 16, v146
	v_and_b32_e32 v145, 0xffff0000, v146
	v_lshlrev_b32_e32 v146, 16, v151
	v_max_f32_e32 v146, v146, v146
	v_max_f32_e32 v146, 0x1e3ce508, v146
	v_pk_mul_f32 v[144:145], v[148:149], v[144:145]
	v_rcp_f32_e32 v148, v146
	v_and_b32_e32 v146, 0xffff0000, v151
	v_max_f32_e32 v146, v146, v146
	v_max_f32_e32 v146, 0x1e3ce508, v146
	v_rcp_f32_e32 v149, v146
	v_pk_mul_f32 v[80:81], v[80:81], v[144:145]
	v_lshlrev_b32_e32 v144, 16, v147
	v_and_b32_e32 v145, 0xffff0000, v147
	v_pk_mul_f32 v[144:145], v[148:149], v[144:145]
	v_lshlrev_b32_e32 v146, 16, v140
	v_and_b32_e32 v140, 0xffff0000, v140
	v_pk_mul_f32 v[82:83], v[82:83], v[144:145]
	v_lshlrev_b32_e32 v144, 16, v136
	v_and_b32_e32 v145, 0xffff0000, v136
	v_lshlrev_b32_e32 v136, 16, v141
	v_max_f32_e32 v140, v140, v140
	v_max_f32_e32 v136, v136, v136
	v_max_f32_e32 v140, 0x1e3ce508, v140
	v_max_f32_e32 v136, 0x1e3ce508, v136
	v_rcp_f32_e32 v147, v140
	v_rcp_f32_e32 v140, v136
	v_and_b32_e32 v136, 0xffff0000, v141
	v_max_f32_e32 v136, v136, v136
	v_max_f32_e32 v136, 0x1e3ce508, v136
	v_rcp_f32_e32 v141, v136
	v_lshlrev_b32_e32 v136, 16, v137
	v_and_b32_e32 v137, 0xffff0000, v137
	v_max_f32_e32 v146, v146, v146
	v_pk_mul_f32 v[136:137], v[140:141], v[136:137]
	v_lshlrev_b32_e32 v140, 16, v142
	v_and_b32_e32 v141, 0xffff0000, v142
	v_max_f32_e32 v140, v140, v140
	v_max_f32_e32 v141, v141, v141
	v_max_f32_e32 v140, 0x1e3ce508, v140
	v_max_f32_e32 v141, 0x1e3ce508, v141
	v_rcp_f32_e32 v140, v140
	v_rcp_f32_e32 v141, v141
	v_pk_mul_f32 v[78:79], v[78:79], v[136:137]
	v_lshlrev_b32_e32 v136, 16, v138
	v_and_b32_e32 v137, 0xffff0000, v138
	v_lshlrev_b32_e32 v138, 16, v143
	v_max_f32_e32 v138, v138, v138
	v_max_f32_e32 v138, 0x1e3ce508, v138
	v_pk_mul_f32 v[136:137], v[140:141], v[136:137]
	v_rcp_f32_e32 v140, v138
	v_and_b32_e32 v138, 0xffff0000, v143
	v_max_f32_e32 v138, v138, v138
	v_max_f32_e32 v138, 0x1e3ce508, v138
	v_rcp_f32_e32 v141, v138
	v_pk_mul_f32 v[72:73], v[72:73], v[136:137]
	v_lshlrev_b32_e32 v136, 16, v139
	v_and_b32_e32 v137, 0xffff0000, v139
	v_pk_mul_f32 v[136:137], v[140:141], v[136:137]
	v_lshlrev_b32_e32 v138, 16, v132
	v_and_b32_e32 v132, 0xffff0000, v132
	v_pk_mul_f32 v[74:75], v[74:75], v[136:137]
	v_lshlrev_b32_e32 v136, 16, v128
	v_and_b32_e32 v137, 0xffff0000, v128
	v_lshlrev_b32_e32 v128, 16, v133
	v_max_f32_e32 v132, v132, v132
	v_max_f32_e32 v128, v128, v128
	v_max_f32_e32 v132, 0x1e3ce508, v132
	v_max_f32_e32 v128, 0x1e3ce508, v128
	v_rcp_f32_e32 v139, v132
	v_rcp_f32_e32 v132, v128
	v_and_b32_e32 v128, 0xffff0000, v133
	v_max_f32_e32 v128, v128, v128
	v_max_f32_e32 v128, 0x1e3ce508, v128
	v_rcp_f32_e32 v133, v128
	v_lshlrev_b32_e32 v128, 16, v129
	v_and_b32_e32 v129, 0xffff0000, v129
	v_max_f32_e32 v138, v138, v138
	v_pk_mul_f32 v[128:129], v[132:133], v[128:129]
	v_lshlrev_b32_e32 v132, 16, v134
	v_and_b32_e32 v133, 0xffff0000, v134
	v_max_f32_e32 v132, v132, v132
	v_max_f32_e32 v133, v133, v133
	v_max_f32_e32 v132, 0x1e3ce508, v132
	v_max_f32_e32 v133, 0x1e3ce508, v133
	v_rcp_f32_e32 v132, v132
	v_rcp_f32_e32 v133, v133
	v_pk_mul_f32 v[70:71], v[70:71], v[128:129]
	v_lshlrev_b32_e32 v128, 16, v130
	v_and_b32_e32 v129, 0xffff0000, v130
	v_lshlrev_b32_e32 v130, 16, v135
	v_max_f32_e32 v130, v130, v130
	v_max_f32_e32 v130, 0x1e3ce508, v130
	v_pk_mul_f32 v[128:129], v[132:133], v[128:129]
	v_rcp_f32_e32 v132, v130
	v_and_b32_e32 v130, 0xffff0000, v135
	v_max_f32_e32 v130, v130, v130
	v_max_f32_e32 v199, 0x1e3ce508, v199
	v_max_f32_e32 v162, 0x1e3ce508, v162
	v_max_f32_e32 v154, 0x1e3ce508, v154
	v_max_f32_e32 v146, 0x1e3ce508, v146
	v_max_f32_e32 v138, 0x1e3ce508, v138
	v_max_f32_e32 v130, 0x1e3ce508, v130
	v_rcp_f32_e32 v202, v199
	v_rcp_f32_e32 v162, v162
	v_rcp_f32_e32 v154, v154
	v_rcp_f32_e32 v146, v146
	v_rcp_f32_e32 v138, v138
	v_rcp_f32_e32 v133, v130
	v_pk_mul_f32 v[64:65], v[64:65], v[128:129]
	v_lshlrev_b32_e32 v128, 16, v131
	v_and_b32_e32 v129, 0xffff0000, v131
	v_pk_mul_f32 v[226:227], v[226:227], v[228:229]
	v_pk_mul_f32 v[200:201], v[202:203], v[200:201]
	v_pk_mul_f32 v[160:161], v[162:163], v[160:161]
	v_pk_mul_f32 v[152:153], v[154:155], v[152:153]
	v_pk_mul_f32 v[144:145], v[146:147], v[144:145]
	v_pk_mul_f32 v[136:137], v[138:139], v[136:137]
	v_pk_mul_f32 v[128:129], v[132:133], v[128:129]
	v_pk_mul_f32 v[124:125], v[124:125], v[226:227]
	v_pk_mul_f32 v[100:101], v[100:101], v[200:201]
	v_pk_mul_f32 v[92:93], v[92:93], v[160:161]
	v_pk_mul_f32 v[84:85], v[84:85], v[152:153]
	v_pk_mul_f32 v[76:77], v[76:77], v[144:145]
	v_pk_mul_f32 v[68:69], v[68:69], v[136:137]
	v_pk_mul_f32 v[66:67], v[66:67], v[128:129]
	v_add_u32_e32 v128, 0x80, v198
	v_mad_i64_i32 v[128:129], s[30:31], v128, s49, v[188:189]
	v_lshl_add_u64 v[128:129], v[128:129], 0, s[28:29]
	v_lshl_add_u64 v[128:129], v[128:129], 0, v[190:191]
	v_lshl_add_u64 v[130:131], v[128:129], 0, s[18:19]
	global_load_dwordx4 v[200:203], v[128:129], off offset:3584
	global_load_dwordx4 v[206:209], v[128:129], off offset:3840
	global_load_dwordx4 v[210:213], v[130:131], off offset:2048
	global_load_dwordx4 v[214:217], v[130:131], off offset:2304
	v_add_u32_e32 v128, 0x90, v198
	v_mad_i64_i32 v[128:129], s[30:31], v128, s49, v[188:189]
	v_lshl_add_u64 v[128:129], v[128:129], 0, s[28:29]
	v_lshl_add_u64 v[128:129], v[128:129], 0, v[190:191]
	v_lshl_add_u64 v[130:131], v[128:129], 0, s[18:19]
	global_load_dwordx4 v[218:221], v[128:129], off offset:3584
	global_load_dwordx4 v[160:163], v[128:129], off offset:3840
	global_load_dwordx4 v[222:225], v[130:131], off offset:2048
	global_load_dwordx4 v[164:167], v[130:131], off offset:2304
	v_add_u32_e32 v128, 0xa0, v198
	v_mad_i64_i32 v[128:129], s[30:31], v128, s49, v[188:189]
	v_lshl_add_u64 v[128:129], v[128:129], 0, s[28:29]
	v_lshl_add_u64 v[128:129], v[128:129], 0, v[190:191]
	v_lshl_add_u64 v[130:131], v[128:129], 0, s[18:19]
	global_load_dwordx4 v[152:155], v[128:129], off offset:3584
	global_load_dwordx4 v[144:147], v[128:129], off offset:3840
	global_load_dwordx4 v[156:159], v[130:131], off offset:2048
	global_load_dwordx4 v[148:151], v[130:131], off offset:2304
	v_add_u32_e32 v128, 0xb0, v198
	v_mad_i64_i32 v[128:129], s[30:31], v128, s49, v[188:189]
	v_lshl_add_u64 v[128:129], v[128:129], 0, s[28:29]
	v_lshl_add_u64 v[128:129], v[128:129], 0, v[190:191]
	v_lshl_add_u64 v[132:133], v[128:129], 0, s[18:19]
	global_load_dwordx4 v[136:139], v[128:129], off offset:3584
	s_nop 0
	global_load_dwordx4 v[128:131], v[128:129], off offset:3840
	s_nop 0
	global_load_dwordx4 v[140:143], v[132:133], off offset:2048
	s_nop 0
	global_load_dwordx4 v[132:135], v[132:133], off offset:2304
	s_waitcnt vmcnt(13)
	v_lshlrev_b32_e32 v188, 16, v210
	v_and_b32_e32 v189, 0xffff0000, v210
	v_max_f32_e32 v188, v188, v188
	v_max_f32_e32 v189, v189, v189
	v_max_f32_e32 v188, 0x1e3ce508, v188
	v_max_f32_e32 v189, 0x1e3ce508, v189
	v_rcp_f32_e32 v188, v188
	v_rcp_f32_e32 v189, v189
	v_lshlrev_b32_e32 v190, 16, v200
	v_and_b32_e32 v191, 0xffff0000, v200
	v_pk_mul_f32 v[188:189], v[188:189], v[190:191]
	v_lshlrev_b32_e32 v190, 16, v211
	v_and_b32_e32 v191, 0xffff0000, v211
	v_max_f32_e32 v190, v190, v190
	v_max_f32_e32 v191, v191, v191
	v_max_f32_e32 v190, 0x1e3ce508, v190
	v_max_f32_e32 v191, 0x1e3ce508, v191
	v_rcp_f32_e32 v190, v190
	v_rcp_f32_e32 v191, v191
	v_pk_mul_f32 v[60:61], v[60:61], v[188:189]
	v_lshlrev_b32_e32 v188, 16, v201
	v_and_b32_e32 v189, 0xffff0000, v201
	v_pk_mul_f32 v[188:189], v[190:191], v[188:189]
	v_lshlrev_b32_e32 v190, 16, v212
	v_and_b32_e32 v191, 0xffff0000, v212
	v_max_f32_e32 v190, v190, v190
	v_max_f32_e32 v191, v191, v191
	v_max_f32_e32 v190, 0x1e3ce508, v190
	v_max_f32_e32 v191, 0x1e3ce508, v191
	v_rcp_f32_e32 v190, v190
	v_rcp_f32_e32 v191, v191
	v_pk_mul_f32 v[62:63], v[62:63], v[188:189]
	v_lshlrev_b32_e32 v188, 16, v202
	v_and_b32_e32 v189, 0xffff0000, v202
	v_pk_mul_f32 v[188:189], v[190:191], v[188:189]
	v_lshlrev_b32_e32 v190, 16, v213
	v_and_b32_e32 v191, 0xffff0000, v213
	v_max_f32_e32 v190, v190, v190
	v_max_f32_e32 v191, v191, v191
	v_max_f32_e32 v190, 0x1e3ce508, v190
	v_max_f32_e32 v191, 0x1e3ce508, v191
	v_rcp_f32_e32 v190, v190
	v_rcp_f32_e32 v191, v191
	v_pk_mul_f32 v[56:57], v[56:57], v[188:189]
	v_lshlrev_b32_e32 v188, 16, v203
	v_and_b32_e32 v189, 0xffff0000, v203
	v_pk_mul_f32 v[188:189], v[190:191], v[188:189]
	s_waitcnt vmcnt(12)
	v_lshlrev_b32_e32 v190, 16, v214
	v_and_b32_e32 v191, 0xffff0000, v214
	v_max_f32_e32 v190, v190, v190
	v_max_f32_e32 v191, v191, v191
	v_max_f32_e32 v190, 0x1e3ce508, v190
	v_max_f32_e32 v191, 0x1e3ce508, v191
	v_rcp_f32_e32 v190, v190
	v_rcp_f32_e32 v191, v191
	v_pk_mul_f32 v[58:59], v[58:59], v[188:189]
	v_lshlrev_b32_e32 v188, 16, v206
	v_and_b32_e32 v189, 0xffff0000, v206
	v_pk_mul_f32 v[188:189], v[190:191], v[188:189]
	v_lshlrev_b32_e32 v190, 16, v215
	v_and_b32_e32 v191, 0xffff0000, v215
	v_max_f32_e32 v190, v190, v190
	v_max_f32_e32 v191, v191, v191
	v_max_f32_e32 v190, 0x1e3ce508, v190
	v_max_f32_e32 v191, 0x1e3ce508, v191
	v_rcp_f32_e32 v190, v190
	v_rcp_f32_e32 v191, v191
	v_pk_mul_f32 v[52:53], v[52:53], v[188:189]
	v_lshlrev_b32_e32 v188, 16, v207
	v_and_b32_e32 v189, 0xffff0000, v207
	v_pk_mul_f32 v[188:189], v[190:191], v[188:189]
	v_lshlrev_b32_e32 v190, 16, v216
	v_and_b32_e32 v191, 0xffff0000, v216
	v_max_f32_e32 v190, v190, v190
	v_max_f32_e32 v191, v191, v191
	v_max_f32_e32 v190, 0x1e3ce508, v190
	v_max_f32_e32 v191, 0x1e3ce508, v191
	v_rcp_f32_e32 v190, v190
	v_rcp_f32_e32 v191, v191
	v_pk_mul_f32 v[54:55], v[54:55], v[188:189]
	v_lshlrev_b32_e32 v188, 16, v208
	v_and_b32_e32 v189, 0xffff0000, v208
	v_pk_mul_f32 v[188:189], v[190:191], v[188:189]
	v_lshlrev_b32_e32 v190, 16, v217
	v_and_b32_e32 v191, 0xffff0000, v217
	v_max_f32_e32 v190, v190, v190
	v_max_f32_e32 v191, v191, v191
	v_max_f32_e32 v190, 0x1e3ce508, v190
	v_max_f32_e32 v191, 0x1e3ce508, v191
	v_rcp_f32_e32 v190, v190
	v_rcp_f32_e32 v191, v191
	v_pk_mul_f32 v[48:49], v[48:49], v[188:189]
	v_lshlrev_b32_e32 v188, 16, v209
	v_and_b32_e32 v189, 0xffff0000, v209
	v_pk_mul_f32 v[188:189], v[190:191], v[188:189]
	s_waitcnt vmcnt(9)
	v_lshlrev_b32_e32 v190, 16, v222
	v_and_b32_e32 v191, 0xffff0000, v222
	v_max_f32_e32 v190, v190, v190
	v_max_f32_e32 v191, v191, v191
	v_max_f32_e32 v190, 0x1e3ce508, v190
	v_max_f32_e32 v191, 0x1e3ce508, v191
	v_rcp_f32_e32 v190, v190
	v_rcp_f32_e32 v191, v191
	v_pk_mul_f32 v[50:51], v[50:51], v[188:189]
	v_lshlrev_b32_e32 v188, 16, v218
	v_and_b32_e32 v189, 0xffff0000, v218
	v_pk_mul_f32 v[188:189], v[190:191], v[188:189]
	v_lshlrev_b32_e32 v190, 16, v223
	v_and_b32_e32 v191, 0xffff0000, v223
	v_max_f32_e32 v190, v190, v190
	v_max_f32_e32 v191, v191, v191
	v_max_f32_e32 v190, 0x1e3ce508, v190
	v_max_f32_e32 v191, 0x1e3ce508, v191
	v_rcp_f32_e32 v190, v190
	v_rcp_f32_e32 v191, v191
	v_pk_mul_f32 v[44:45], v[44:45], v[188:189]
	v_lshlrev_b32_e32 v188, 16, v219
	v_and_b32_e32 v189, 0xffff0000, v219
	v_pk_mul_f32 v[188:189], v[190:191], v[188:189]
	v_lshlrev_b32_e32 v190, 16, v224
	v_and_b32_e32 v191, 0xffff0000, v224
	v_max_f32_e32 v190, v190, v190
	v_max_f32_e32 v191, v191, v191
	v_max_f32_e32 v190, 0x1e3ce508, v190
	v_max_f32_e32 v191, 0x1e3ce508, v191
	v_rcp_f32_e32 v190, v190
	v_rcp_f32_e32 v191, v191
	v_pk_mul_f32 v[46:47], v[46:47], v[188:189]
	v_lshlrev_b32_e32 v188, 16, v220
	v_and_b32_e32 v189, 0xffff0000, v220
	v_pk_mul_f32 v[188:189], v[190:191], v[188:189]
	v_lshlrev_b32_e32 v190, 16, v225
	v_and_b32_e32 v191, 0xffff0000, v225
	v_max_f32_e32 v190, v190, v190
	v_max_f32_e32 v191, v191, v191
	v_max_f32_e32 v190, 0x1e3ce508, v190
	v_max_f32_e32 v191, 0x1e3ce508, v191
	v_rcp_f32_e32 v190, v190
	v_rcp_f32_e32 v191, v191
	v_pk_mul_f32 v[40:41], v[40:41], v[188:189]
	v_lshlrev_b32_e32 v188, 16, v221
	v_and_b32_e32 v189, 0xffff0000, v221
	v_pk_mul_f32 v[188:189], v[190:191], v[188:189]
	s_waitcnt vmcnt(8)
	v_lshlrev_b32_e32 v190, 16, v164
	v_and_b32_e32 v164, 0xffff0000, v164
	v_pk_mul_f32 v[42:43], v[42:43], v[188:189]
	v_lshlrev_b32_e32 v188, 16, v160
	v_and_b32_e32 v189, 0xffff0000, v160
	v_lshlrev_b32_e32 v160, 16, v165
	v_max_f32_e32 v164, v164, v164
	v_max_f32_e32 v160, v160, v160
	v_max_f32_e32 v164, 0x1e3ce508, v164
	v_max_f32_e32 v160, 0x1e3ce508, v160
	v_rcp_f32_e32 v191, v164
	v_rcp_f32_e32 v164, v160
	v_and_b32_e32 v160, 0xffff0000, v165
	v_max_f32_e32 v160, v160, v160
	v_max_f32_e32 v160, 0x1e3ce508, v160
	v_rcp_f32_e32 v165, v160
	v_lshlrev_b32_e32 v160, 16, v161
	v_and_b32_e32 v161, 0xffff0000, v161
	v_max_f32_e32 v190, v190, v190
	v_pk_mul_f32 v[160:161], v[164:165], v[160:161]
	v_lshlrev_b32_e32 v164, 16, v166
	v_and_b32_e32 v165, 0xffff0000, v166
	v_max_f32_e32 v164, v164, v164
	v_max_f32_e32 v165, v165, v165
	v_max_f32_e32 v164, 0x1e3ce508, v164
	v_max_f32_e32 v165, 0x1e3ce508, v165
	v_rcp_f32_e32 v164, v164
	v_rcp_f32_e32 v165, v165
	v_pk_mul_f32 v[38:39], v[38:39], v[160:161]
	v_lshlrev_b32_e32 v160, 16, v162
	v_and_b32_e32 v161, 0xffff0000, v162
	v_lshlrev_b32_e32 v162, 16, v167
	v_max_f32_e32 v162, v162, v162
	v_max_f32_e32 v162, 0x1e3ce508, v162
	v_pk_mul_f32 v[160:161], v[164:165], v[160:161]
	v_rcp_f32_e32 v164, v162
	v_and_b32_e32 v162, 0xffff0000, v167
	v_max_f32_e32 v162, v162, v162
	v_max_f32_e32 v162, 0x1e3ce508, v162
	v_rcp_f32_e32 v165, v162
	v_pk_mul_f32 v[32:33], v[32:33], v[160:161]
	v_lshlrev_b32_e32 v160, 16, v163
	v_and_b32_e32 v161, 0xffff0000, v163
	v_pk_mul_f32 v[160:161], v[164:165], v[160:161]
	s_waitcnt vmcnt(5)
	v_lshlrev_b32_e32 v162, 16, v156
	v_and_b32_e32 v156, 0xffff0000, v156
	v_pk_mul_f32 v[34:35], v[34:35], v[160:161]
	v_lshlrev_b32_e32 v160, 16, v152
	v_and_b32_e32 v161, 0xffff0000, v152
	v_lshlrev_b32_e32 v152, 16, v157
	v_max_f32_e32 v156, v156, v156
	v_max_f32_e32 v152, v152, v152
	v_max_f32_e32 v156, 0x1e3ce508, v156
	v_max_f32_e32 v152, 0x1e3ce508, v152
	v_rcp_f32_e32 v163, v156
	v_rcp_f32_e32 v156, v152
	v_and_b32_e32 v152, 0xffff0000, v157
	v_max_f32_e32 v152, v152, v152
	v_max_f32_e32 v152, 0x1e3ce508, v152
	v_rcp_f32_e32 v157, v152
	v_lshlrev_b32_e32 v152, 16, v153
	v_and_b32_e32 v153, 0xffff0000, v153
	v_max_f32_e32 v162, v162, v162
	v_pk_mul_f32 v[152:153], v[156:157], v[152:153]
	v_lshlrev_b32_e32 v156, 16, v158
	v_and_b32_e32 v157, 0xffff0000, v158
	v_max_f32_e32 v156, v156, v156
	v_max_f32_e32 v157, v157, v157
	v_max_f32_e32 v156, 0x1e3ce508, v156
	v_max_f32_e32 v157, 0x1e3ce508, v157
	v_rcp_f32_e32 v156, v156
	v_rcp_f32_e32 v157, v157
	v_pk_mul_f32 v[30:31], v[30:31], v[152:153]
	v_lshlrev_b32_e32 v152, 16, v154
	v_and_b32_e32 v153, 0xffff0000, v154
	v_lshlrev_b32_e32 v154, 16, v159
	v_max_f32_e32 v154, v154, v154
	v_max_f32_e32 v154, 0x1e3ce508, v154
	v_pk_mul_f32 v[152:153], v[156:157], v[152:153]
	v_rcp_f32_e32 v156, v154
	v_and_b32_e32 v154, 0xffff0000, v159
	v_max_f32_e32 v154, v154, v154
	v_max_f32_e32 v154, 0x1e3ce508, v154
	v_rcp_f32_e32 v157, v154
	v_pk_mul_f32 v[24:25], v[24:25], v[152:153]
	v_lshlrev_b32_e32 v152, 16, v155
	v_and_b32_e32 v153, 0xffff0000, v155
	v_pk_mul_f32 v[152:153], v[156:157], v[152:153]
	s_waitcnt vmcnt(4)
	v_lshlrev_b32_e32 v154, 16, v148
	v_and_b32_e32 v148, 0xffff0000, v148
	v_pk_mul_f32 v[26:27], v[26:27], v[152:153]
	v_lshlrev_b32_e32 v152, 16, v144
	v_and_b32_e32 v153, 0xffff0000, v144
	v_lshlrev_b32_e32 v144, 16, v149
	v_max_f32_e32 v148, v148, v148
	v_max_f32_e32 v144, v144, v144
	v_max_f32_e32 v148, 0x1e3ce508, v148
	v_max_f32_e32 v144, 0x1e3ce508, v144
	v_rcp_f32_e32 v155, v148
	v_rcp_f32_e32 v148, v144
	v_and_b32_e32 v144, 0xffff0000, v149
	v_max_f32_e32 v144, v144, v144
	v_max_f32_e32 v144, 0x1e3ce508, v144
	v_rcp_f32_e32 v149, v144
	v_lshlrev_b32_e32 v144, 16, v145
	v_and_b32_e32 v145, 0xffff0000, v145
	v_max_f32_e32 v154, v154, v154
	v_pk_mul_f32 v[144:145], v[148:149], v[144:145]
	v_lshlrev_b32_e32 v148, 16, v150
	v_and_b32_e32 v149, 0xffff0000, v150
	v_max_f32_e32 v148, v148, v148
	v_max_f32_e32 v149, v149, v149
	v_max_f32_e32 v148, 0x1e3ce508, v148
	v_max_f32_e32 v149, 0x1e3ce508, v149
	v_rcp_f32_e32 v148, v148
	v_rcp_f32_e32 v149, v149
	v_pk_mul_f32 v[22:23], v[22:23], v[144:145]
	v_lshlrev_b32_e32 v144, 16, v146
	v_and_b32_e32 v145, 0xffff0000, v146
	v_lshlrev_b32_e32 v146, 16, v151
	v_max_f32_e32 v146, v146, v146
	v_max_f32_e32 v146, 0x1e3ce508, v146
	v_pk_mul_f32 v[144:145], v[148:149], v[144:145]
	v_rcp_f32_e32 v148, v146
	v_and_b32_e32 v146, 0xffff0000, v151
	v_max_f32_e32 v146, v146, v146
	v_max_f32_e32 v146, 0x1e3ce508, v146
	v_rcp_f32_e32 v149, v146
	v_pk_mul_f32 v[16:17], v[16:17], v[144:145]
	v_lshlrev_b32_e32 v144, 16, v147
	v_and_b32_e32 v145, 0xffff0000, v147
	v_pk_mul_f32 v[144:145], v[148:149], v[144:145]
	s_waitcnt vmcnt(1)
	v_lshlrev_b32_e32 v146, 16, v140
	v_and_b32_e32 v140, 0xffff0000, v140
	v_pk_mul_f32 v[18:19], v[18:19], v[144:145]
	v_lshlrev_b32_e32 v144, 16, v136
	v_and_b32_e32 v145, 0xffff0000, v136
	v_lshlrev_b32_e32 v136, 16, v141
	v_max_f32_e32 v140, v140, v140
	v_max_f32_e32 v136, v136, v136
	v_max_f32_e32 v140, 0x1e3ce508, v140
	v_max_f32_e32 v136, 0x1e3ce508, v136
	v_rcp_f32_e32 v147, v140
	v_rcp_f32_e32 v140, v136
	v_and_b32_e32 v136, 0xffff0000, v141
	v_max_f32_e32 v136, v136, v136
	v_max_f32_e32 v136, 0x1e3ce508, v136
	v_rcp_f32_e32 v141, v136
	v_lshlrev_b32_e32 v136, 16, v137
	v_and_b32_e32 v137, 0xffff0000, v137
	v_max_f32_e32 v146, v146, v146
	v_pk_mul_f32 v[136:137], v[140:141], v[136:137]
	v_lshlrev_b32_e32 v140, 16, v142
	v_and_b32_e32 v141, 0xffff0000, v142
	v_max_f32_e32 v140, v140, v140
	v_max_f32_e32 v141, v141, v141
	v_max_f32_e32 v140, 0x1e3ce508, v140
	v_max_f32_e32 v141, 0x1e3ce508, v141
	v_rcp_f32_e32 v140, v140
	v_rcp_f32_e32 v141, v141
	v_pk_mul_f32 v[14:15], v[14:15], v[136:137]
	v_lshlrev_b32_e32 v136, 16, v138
	v_and_b32_e32 v137, 0xffff0000, v138
	v_lshlrev_b32_e32 v138, 16, v143
	v_max_f32_e32 v138, v138, v138
	v_max_f32_e32 v138, 0x1e3ce508, v138
	v_pk_mul_f32 v[136:137], v[140:141], v[136:137]
	v_rcp_f32_e32 v140, v138
	v_and_b32_e32 v138, 0xffff0000, v143
	v_max_f32_e32 v138, v138, v138
	v_max_f32_e32 v138, 0x1e3ce508, v138
	v_rcp_f32_e32 v141, v138
	v_pk_mul_f32 v[8:9], v[8:9], v[136:137]
	v_lshlrev_b32_e32 v136, 16, v139
	v_and_b32_e32 v137, 0xffff0000, v139
	v_pk_mul_f32 v[136:137], v[140:141], v[136:137]
	s_waitcnt vmcnt(0)
	v_lshlrev_b32_e32 v138, 16, v132
	v_and_b32_e32 v132, 0xffff0000, v132
	v_pk_mul_f32 v[10:11], v[10:11], v[136:137]
	v_lshlrev_b32_e32 v136, 16, v128
	v_and_b32_e32 v137, 0xffff0000, v128
	v_lshlrev_b32_e32 v128, 16, v133
	v_max_f32_e32 v132, v132, v132
	v_max_f32_e32 v128, v128, v128
	v_max_f32_e32 v132, 0x1e3ce508, v132
	v_max_f32_e32 v128, 0x1e3ce508, v128
	v_rcp_f32_e32 v139, v132
	v_rcp_f32_e32 v132, v128
	v_and_b32_e32 v128, 0xffff0000, v133
	v_max_f32_e32 v128, v128, v128
	v_max_f32_e32 v128, 0x1e3ce508, v128
	v_rcp_f32_e32 v133, v128
	v_lshlrev_b32_e32 v128, 16, v129
	v_and_b32_e32 v129, 0xffff0000, v129
	v_max_f32_e32 v138, v138, v138
	v_pk_mul_f32 v[128:129], v[132:133], v[128:129]
	v_lshlrev_b32_e32 v132, 16, v134
	v_and_b32_e32 v133, 0xffff0000, v134
	v_max_f32_e32 v132, v132, v132
	v_max_f32_e32 v133, v133, v133
	v_max_f32_e32 v132, 0x1e3ce508, v132
	v_max_f32_e32 v133, 0x1e3ce508, v133
	v_rcp_f32_e32 v132, v132
	v_rcp_f32_e32 v133, v133
	v_pk_mul_f32 v[6:7], v[6:7], v[128:129]
	v_lshlrev_b32_e32 v128, 16, v130
	v_and_b32_e32 v129, 0xffff0000, v130
	v_lshlrev_b32_e32 v130, 16, v135
	v_max_f32_e32 v130, v130, v130
	v_max_f32_e32 v130, 0x1e3ce508, v130
	v_pk_mul_f32 v[128:129], v[132:133], v[128:129]
	v_rcp_f32_e32 v132, v130
	v_and_b32_e32 v130, 0xffff0000, v135
	v_max_f32_e32 v130, v130, v130
	v_max_f32_e32 v190, 0x1e3ce508, v190
	v_max_f32_e32 v162, 0x1e3ce508, v162
	v_max_f32_e32 v154, 0x1e3ce508, v154
	v_max_f32_e32 v146, 0x1e3ce508, v146
	v_max_f32_e32 v138, 0x1e3ce508, v138
	v_max_f32_e32 v130, 0x1e3ce508, v130
	v_rcp_f32_e32 v190, v190
	v_rcp_f32_e32 v162, v162
	v_rcp_f32_e32 v154, v154
	v_rcp_f32_e32 v146, v146
	v_rcp_f32_e32 v138, v138
	v_rcp_f32_e32 v133, v130
	v_pk_mul_f32 v[0:1], v[0:1], v[128:129]
	v_lshlrev_b32_e32 v128, 16, v131
	v_and_b32_e32 v129, 0xffff0000, v131
	v_pk_mul_f32 v[188:189], v[190:191], v[188:189]
	v_pk_mul_f32 v[160:161], v[162:163], v[160:161]
	v_pk_mul_f32 v[152:153], v[154:155], v[152:153]
	v_pk_mul_f32 v[144:145], v[146:147], v[144:145]
	v_pk_mul_f32 v[136:137], v[138:139], v[136:137]
	v_pk_mul_f32 v[128:129], v[132:133], v[128:129]
	v_pk_mul_f32 v[36:37], v[36:37], v[188:189]
	v_pk_mul_f32 v[28:29], v[28:29], v[160:161]
	v_pk_mul_f32 v[20:21], v[20:21], v[152:153]
	v_pk_mul_f32 v[12:13], v[12:13], v[144:145]
	v_pk_mul_f32 v[4:5], v[4:5], v[136:137]
	v_pk_mul_f32 v[2:3], v[2:3], v[128:129]
	s_andn2_b64 vcc, exec, s[8:9]
	s_cbranch_vccnz .Lhk_b_1
	s_barrier
.Lhk_b_1:
	s_branch .LBB0_1003
.LBB0_1010:
	s_and_b64 vcc, exec, s[16:17]
	s_cbranch_vccz .LBB0_1012
	s_barrier

.Lhk_a_2:
	v_mov_b32_e32 v128, v193
	v_mov_b32_e32 v129, v192
	s_and_b32 s6, s26, 0xc00
	v_add_u32_e32 v198, s59, v129
	v_mov_b64_e32 v[188:189], s[10:11]
	v_lshl_add_u32 v128, v128, 3, s58
	s_addk_i32 s6, 0xfc00
	v_mad_i64_i32 v[130:131], s[28:29], v198, s49, v[188:189]
	v_ashrrev_i32_e32 v129, 31, v128
	s_lshl_b64 s[28:29], s[6:7], 1
	v_lshl_add_u64 v[130:131], v[130:131], 0, s[28:29]
	v_lshlrev_b64 v[190:191], 1, v[128:129]
	v_lshl_add_u64 v[128:129], v[130:131], 0, v[190:191]
	v_lshl_add_u64 v[130:131], v[128:129], 0, s[18:19]
	global_load_dwordx4 v[200:203], v[128:129], off offset:3584
	global_load_dwordx4 v[206:209], v[128:129], off offset:3840
	global_load_dwordx4 v[210:213], v[130:131], off offset:2048
	global_load_dwordx4 v[214:217], v[130:131], off offset:2304
	v_add_u32_e32 v128, 16, v198
	v_mad_i64_i32 v[128:129], s[30:31], v128, s49, v[188:189]
	v_lshl_add_u64 v[128:129], v[128:129], 0, s[28:29]
	v_lshl_add_u64 v[128:129], v[128:129], 0, v[190:191]
	v_lshl_add_u64 v[130:131], v[128:129], 0, s[18:19]
	global_load_dwordx4 v[218:221], v[128:129], off offset:3584
	global_load_dwordx4 v[160:163], v[128:129], off offset:3840
	global_load_dwordx4 v[222:225], v[130:131], off offset:2048
	global_load_dwordx4 v[164:167], v[130:131], off offset:2304
	v_add_u32_e32 v128, 32, v198
	v_mad_i64_i32 v[128:129], s[30:31], v128, s49, v[188:189]
	v_lshl_add_u64 v[128:129], v[128:129], 0, s[28:29]
	v_lshl_add_u64 v[128:129], v[128:129], 0, v[190:191]
	v_lshl_add_u64 v[130:131], v[128:129], 0, s[18:19]
	global_load_dwordx4 v[152:155], v[128:129], off offset:3584
	global_load_dwordx4 v[144:147], v[128:129], off offset:3840
	global_load_dwordx4 v[156:159], v[130:131], off offset:2048
	global_load_dwordx4 v[148:151], v[130:131], off offset:2304
	v_add_u32_e32 v128, 48, v198
	v_mad_i64_i32 v[128:129], s[30:31], v128, s49, v[188:189]
	v_lshl_add_u64 v[128:129], v[128:129], 0, s[28:29]
	v_lshl_add_u64 v[128:129], v[128:129], 0, v[190:191]
	v_lshl_add_u64 v[132:133], v[128:129], 0, s[18:19]
	global_load_dwordx4 v[136:139], v[128:129], off offset:3584
	s_nop 0
	global_load_dwordx4 v[128:131], v[128:129], off offset:3840
	s_nop 0
	global_load_dwordx4 v[140:143], v[132:133], off offset:2048
	s_nop 0
	global_load_dwordx4 v[132:135], v[132:133], off offset:2304
	s_waitcnt vmcnt(0)
	v_lshlrev_b32_e32 v199, 16, v210
	v_max_f32_e32 v199, v199, v199
	v_max_f32_e32 v199, 0x1e3ce508, v199
	v_rcp_f32_e32 v226, v199
	v_and_b32_e32 v199, 0xffff0000, v210
	v_max_f32_e32 v199, v199, v199
	v_max_f32_e32 v199, 0x1e3ce508, v199
	v_rcp_f32_e32 v227, v199
	v_lshlrev_b32_e32 v199, 16, v211
	v_max_f32_e32 v199, v199, v199
	v_max_f32_e32 v199, 0x1e3ce508, v199
	v_rcp_f32_e32 v210, v199
	v_and_b32_e32 v199, 0xffff0000, v211
	v_max_f32_e32 v199, v199, v199
	v_max_f32_e32 v199, 0x1e3ce508, v199
	v_rcp_f32_e32 v211, v199
	v_lshlrev_b32_e32 v199, 16, v212
	v_max_f32_e32 v199, v199, v199
	v_lshlrev_b32_e32 v228, 16, v200
	v_and_b32_e32 v229, 0xffff0000, v200
	v_lshlrev_b32_e32 v200, 16, v201
	v_and_b32_e32 v201, 0xffff0000, v201
	v_max_f32_e32 v199, 0x1e3ce508, v199
	v_pk_mul_f32 v[200:201], v[210:211], v[200:201]
	v_rcp_f32_e32 v210, v199
	v_and_b32_e32 v199, 0xffff0000, v212
	v_max_f32_e32 v199, v199, v199
	v_max_f32_e32 v199, 0x1e3ce508, v199
	v_rcp_f32_e32 v211, v199
	v_lshlrev_b32_e32 v199, 16, v213
	v_max_f32_e32 v199, v199, v199
	v_pk_mul_f32 v[126:127], v[126:127], v[200:201]
	v_lshlrev_b32_e32 v200, 16, v202
	v_and_b32_e32 v201, 0xffff0000, v202
	v_max_f32_e32 v199, 0x1e3ce508, v199
	v_pk_mul_f32 v[200:201], v[210:211], v[200:201]
	v_rcp_f32_e32 v210, v199
	v_and_b32_e32 v199, 0xffff0000, v213
	v_max_f32_e32 v199, v199, v199
	v_max_f32_e32 v199, 0x1e3ce508, v199
	v_rcp_f32_e32 v211, v199
	v_lshlrev_b32_e32 v199, 16, v214
	v_max_f32_e32 v199, v199, v199
	v_max_f32_e32 v199, 0x1e3ce508, v199
	v_rcp_f32_e32 v202, v199
	v_and_b32_e32 v199, 0xffff0000, v214
	v_max_f32_e32 v199, v199, v199
	v_max_f32_e32 v199, 0x1e3ce508, v199
	v_pk_mul_f32 v[120:121], v[120:121], v[200:201]
	v_lshlrev_b32_e32 v200, 16, v203
	v_and_b32_e32 v201, 0xffff0000, v203
	v_rcp_f32_e32 v203, v199
	v_lshlrev_b32_e32 v199, 16, v215
	v_pk_mul_f32 v[200:201], v[210:211], v[200:201]
	v_max_f32_e32 v199, v199, v199
	v_pk_mul_f32 v[122:123], v[122:123], v[200:201]
	v_lshlrev_b32_e32 v200, 16, v206
	v_and_b32_e32 v201, 0xffff0000, v206
	v_max_f32_e32 v199, 0x1e3ce508, v199
	v_pk_mul_f32 v[200:201], v[202:203], v[200:201]
	v_rcp_f32_e32 v202, v199
	v_and_b32_e32 v199, 0xffff0000, v215
	v_max_f32_e32 v199, v199, v199
	v_max_f32_e32 v199, 0x1e3ce508, v199
	v_rcp_f32_e32 v203, v199
	v_lshlrev_b32_e32 v199, 16, v216
	v_max_f32_e32 v199, v199, v199
	v_pk_mul_f32 v[116:117], v[116:117], v[200:201]
	v_lshlrev_b32_e32 v200, 16, v207
	v_and_b32_e32 v201, 0xffff0000, v207
	v_max_f32_e32 v199, 0x1e3ce508, v199
	v_pk_mul_f32 v[200:201], v[202:203], v[200:201]
	v_rcp_f32_e32 v202, v199
	v_and_b32_e32 v199, 0xffff0000, v216
	v_max_f32_e32 v199, v199, v199
	v_max_f32_e32 v199, 0x1e3ce508, v199
	v_rcp_f32_e32 v203, v199
	v_lshlrev_b32_e32 v199, 16, v217
	v_max_f32_e32 v199, v199, v199
	v_pk_mul_f32 v[118:119], v[118:119], v[200:201]
	v_lshlrev_b32_e32 v200, 16, v208
	v_and_b32_e32 v201, 0xffff0000, v208
	v_max_f32_e32 v199, 0x1e3ce508, v199
	v_pk_mul_f32 v[200:201], v[202:203], v[200:201]
	v_rcp_f32_e32 v202, v199
	v_and_b32_e32 v199, 0xffff0000, v217
	v_max_f32_e32 v199, v199, v199
	v_max_f32_e32 v199, 0x1e3ce508, v199
	v_rcp_f32_e32 v203, v199
	v_lshlrev_b32_e32 v199, 16, v222
	v_max_f32_e32 v199, v199, v199
	v_pk_mul_f32 v[112:113], v[112:113], v[200:201]
	v_lshlrev_b32_e32 v200, 16, v209
	v_and_b32_e32 v201, 0xffff0000, v209
	v_max_f32_e32 v199, 0x1e3ce508, v199
	v_pk_mul_f32 v[200:201], v[202:203], v[200:201]
	v_rcp_f32_e32 v202, v199
	v_and_b32_e32 v199, 0xffff0000, v222
	v_max_f32_e32 v199, v199, v199
	v_max_f32_e32 v199, 0x1e3ce508, v199
	v_rcp_f32_e32 v203, v199
	v_lshlrev_b32_e32 v199, 16, v223
	v_max_f32_e32 v199, v199, v199
	v_pk_mul_f32 v[114:115], v[114:115], v[200:201]
	v_lshlrev_b32_e32 v200, 16, v218
	v_and_b32_e32 v201, 0xffff0000, v218
	v_max_f32_e32 v199, 0x1e3ce508, v199
	v_pk_mul_f32 v[200:201], v[202:203], v[200:201]
	v_rcp_f32_e32 v202, v199
	v_and_b32_e32 v199, 0xffff0000, v223
	v_max_f32_e32 v199, v199, v199
	v_max_f32_e32 v199, 0x1e3ce508, v199
	v_rcp_f32_e32 v203, v199
	v_lshlrev_b32_e32 v199, 16, v224
	v_max_f32_e32 v199, v199, v199
	v_pk_mul_f32 v[108:109], v[108:109], v[200:201]
	v_lshlrev_b32_e32 v200, 16, v219
	v_and_b32_e32 v201, 0xffff0000, v219
	v_max_f32_e32 v199, 0x1e3ce508, v199
	v_pk_mul_f32 v[200:201], v[202:203], v[200:201]
	v_rcp_f32_e32 v202, v199
	v_and_b32_e32 v199, 0xffff0000, v224
	v_max_f32_e32 v199, v199, v199
	v_max_f32_e32 v199, 0x1e3ce508, v199
	v_rcp_f32_e32 v203, v199
	v_lshlrev_b32_e32 v199, 16, v225
	v_max_f32_e32 v199, v199, v199
	v_pk_mul_f32 v[110:111], v[110:111], v[200:201]
	v_lshlrev_b32_e32 v200, 16, v220
	v_and_b32_e32 v201, 0xffff0000, v220
	v_max_f32_e32 v199, 0x1e3ce508, v199
	v_pk_mul_f32 v[200:201], v[202:203], v[200:201]
	v_rcp_f32_e32 v202, v199
	v_and_b32_e32 v199, 0xffff0000, v225
	v_max_f32_e32 v199, v199, v199
	v_max_f32_e32 v199, 0x1e3ce508, v199
	v_rcp_f32_e32 v203, v199
	v_pk_mul_f32 v[104:105], v[104:105], v[200:201]
	v_lshlrev_b32_e32 v200, 16, v221
	v_and_b32_e32 v201, 0xffff0000, v221
	v_pk_mul_f32 v[200:201], v[202:203], v[200:201]
	v_lshlrev_b32_e32 v199, 16, v164
	v_and_b32_e32 v164, 0xffff0000, v164
	v_pk_mul_f32 v[106:107], v[106:107], v[200:201]
	v_lshlrev_b32_e32 v200, 16, v160
	v_and_b32_e32 v201, 0xffff0000, v160
	v_lshlrev_b32_e32 v160, 16, v165
	v_max_f32_e32 v164, v164, v164
	v_max_f32_e32 v160, v160, v160
	v_max_f32_e32 v164, 0x1e3ce508, v164
	v_max_f32_e32 v160, 0x1e3ce508, v160
	v_rcp_f32_e32 v203, v164
	v_rcp_f32_e32 v164, v160
	v_and_b32_e32 v160, 0xffff0000, v165
	v_max_f32_e32 v160, v160, v160
	v_max_f32_e32 v160, 0x1e3ce508, v160
	v_rcp_f32_e32 v165, v160
	v_lshlrev_b32_e32 v160, 16, v161
	v_and_b32_e32 v161, 0xffff0000, v161
	v_max_f32_e32 v199, v199, v199
	v_pk_mul_f32 v[160:161], v[164:165], v[160:161]
	v_lshlrev_b32_e32 v164, 16, v166
	v_and_b32_e32 v165, 0xffff0000, v166
	v_max_f32_e32 v164, v164, v164
	v_max_f32_e32 v165, v165, v165
	v_max_f32_e32 v164, 0x1e3ce508, v164
	v_max_f32_e32 v165, 0x1e3ce508, v165
	v_rcp_f32_e32 v164, v164
	v_rcp_f32_e32 v165, v165
	v_pk_mul_f32 v[102:103], v[102:103], v[160:161]
	v_lshlrev_b32_e32 v160, 16, v162
	v_and_b32_e32 v161, 0xffff0000, v162
	v_lshlrev_b32_e32 v162, 16, v167
	v_max_f32_e32 v162, v162, v162
	v_max_f32_e32 v162, 0x1e3ce508, v162
	v_pk_mul_f32 v[160:161], v[164:165], v[160:161]
	v_rcp_f32_e32 v164, v162
	v_and_b32_e32 v162, 0xffff0000, v167
	v_max_f32_e32 v162, v162, v162
	v_max_f32_e32 v162, 0x1e3ce508, v162
	v_rcp_f32_e32 v165, v162
	v_pk_mul_f32 v[96:97], v[96:97], v[160:161]
	v_lshlrev_b32_e32 v160, 16, v163
	v_and_b32_e32 v161, 0xffff0000, v163
	v_pk_mul_f32 v[160:161], v[164:165], v[160:161]
	v_lshlrev_b32_e32 v162, 16, v156
	v_and_b32_e32 v156, 0xffff0000, v156
	v_pk_mul_f32 v[98:99], v[98:99], v[160:161]
	v_lshlrev_b32_e32 v160, 16, v152
	v_and_b32_e32 v161, 0xffff0000, v152
	v_lshlrev_b32_e32 v152, 16, v157
	v_max_f32_e32 v156, v156, v156
	v_max_f32_e32 v152, v152, v152
	v_max_f32_e32 v156, 0x1e3ce508, v156
	v_max_f32_e32 v152, 0x1e3ce508, v152
	v_rcp_f32_e32 v163, v156
	v_rcp_f32_e32 v156, v152
	v_and_b32_e32 v152, 0xffff0000, v157
	v_max_f32_e32 v152, v152, v152
	v_max_f32_e32 v152, 0x1e3ce508, v152
	v_rcp_f32_e32 v157, v152
	v_lshlrev_b32_e32 v152, 16, v153
	v_and_b32_e32 v153, 0xffff0000, v153
	v_max_f32_e32 v162, v162, v162
	v_pk_mul_f32 v[152:153], v[156:157], v[152:153]
	v_lshlrev_b32_e32 v156, 16, v158
	v_and_b32_e32 v157, 0xffff0000, v158
	v_max_f32_e32 v156, v156, v156
	v_max_f32_e32 v157, v157, v157
	v_max_f32_e32 v156, 0x1e3ce508, v156
	v_max_f32_e32 v157, 0x1e3ce508, v157
	v_rcp_f32_e32 v156, v156
	v_rcp_f32_e32 v157, v157
	v_pk_mul_f32 v[94:95], v[94:95], v[152:153]
	v_lshlrev_b32_e32 v152, 16, v154
	v_and_b32_e32 v153, 0xffff0000, v154
	v_lshlrev_b32_e32 v154, 16, v159
	v_max_f32_e32 v154, v154, v154
	v_max_f32_e32 v154, 0x1e3ce508, v154
	v_pk_mul_f32 v[152:153], v[156:157], v[152:153]
	v_rcp_f32_e32 v156, v154
	v_and_b32_e32 v154, 0xffff0000, v159
	v_max_f32_e32 v154, v154, v154
	v_max_f32_e32 v154, 0x1e3ce508, v154
	v_rcp_f32_e32 v157, v154
	v_pk_mul_f32 v[88:89], v[88:89], v[152:153]
	v_lshlrev_b32_e32 v152, 16, v155
	v_and_b32_e32 v153, 0xffff0000, v155
	v_pk_mul_f32 v[152:153], v[156:157], v[152:153]
	v_lshlrev_b32_e32 v154, 16, v148
	v_and_b32_e32 v148, 0xffff0000, v148
	v_pk_mul_f32 v[90:91], v[90:91], v[152:153]
	v_lshlrev_b32_e32 v152, 16, v144
	v_and_b32_e32 v153, 0xffff0000, v144
	v_lshlrev_b32_e32 v144, 16, v149
	v_max_f32_e32 v148, v148, v148
	v_max_f32_e32 v144, v144, v144
	v_max_f32_e32 v148, 0x1e3ce508, v148
	v_max_f32_e32 v144, 0x1e3ce508, v144
	v_rcp_f32_e32 v155, v148
	v_rcp_f32_e32 v148, v144
	v_and_b32_e32 v144, 0xffff0000, v149
	v_max_f32_e32 v144, v144, v144
	v_max_f32_e32 v144, 0x1e3ce508, v144
	v_rcp_f32_e32 v149, v144
	v_lshlrev_b32_e32 v144, 16, v145
	v_and_b32_e32 v145, 0xffff0000, v145
	v_max_f32_e32 v154, v154, v154
	v_pk_mul_f32 v[144:145], v[148:149], v[144:145]
	v_lshlrev_b32_e32 v148, 16, v150
	v_and_b32_e32 v149, 0xffff0000, v150
	v_max_f32_e32 v148, v148, v148
	v_max_f32_e32 v149, v149, v149
	v_max_f32_e32 v148, 0x1e3ce508, v148
	v_max_f32_e32 v149, 0x1e3ce508, v149
	v_rcp_f32_e32 v148, v148
	v_rcp_f32_e32 v149, v149
	v_pk_mul_f32 v[86:87], v[86:87], v[144:145]
	v_lshlrev_b32_e32 v144, 16, v146
	v_and_b32_e32 v145, 0xffff0000, v146
	v_lshlrev_b32_e32 v146, 16, v151
	v_max_f32_e32 v146, v146, v146
	v_max_f32_e32 v146, 0x1e3ce508, v146
	v_pk_mul_f32 v[144:145], v[148:149], v[144:145]
	v_rcp_f32_e32 v148, v146
	v_and_b32_e32 v146, 0xffff0000, v151
	v_max_f32_e32 v146, v146, v146
	v_max_f32_e32 v146, 0x1e3ce508, v146
	v_rcp_f32_e32 v149, v146
	v_pk_mul_f32 v[80:81], v[80:81], v[144:145]
	v_lshlrev_b32_e32 v144, 16, v147
	v_and_b32_e32 v145, 0xffff0000, v147
	v_pk_mul_f32 v[144:145], v[148:149], v[144:145]
	v_lshlrev_b32_e32 v146, 16, v140
	v_and_b32_e32 v140, 0xffff0000, v140
	v_pk_mul_f32 v[82:83], v[82:83], v[144:145]
	v_lshlrev_b32_e32 v144, 16, v136
	v_and_b32_e32 v145, 0xffff0000, v136
	v_lshlrev_b32_e32 v136, 16, v141
	v_max_f32_e32 v140, v140, v140
	v_max_f32_e32 v136, v136, v136
	v_max_f32_e32 v140, 0x1e3ce508, v140
	v_max_f32_e32 v136, 0x1e3ce508, v136
	v_rcp_f32_e32 v147, v140
	v_rcp_f32_e32 v140, v136
	v_and_b32_e32 v136, 0xffff0000, v141
	v_max_f32_e32 v136, v136, v136
	v_max_f32_e32 v136, 0x1e3ce508, v136
	v_rcp_f32_e32 v141, v136
	v_lshlrev_b32_e32 v136, 16, v137
	v_and_b32_e32 v137, 0xffff0000, v137
	v_max_f32_e32 v146, v146, v146
	v_pk_mul_f32 v[136:137], v[140:141], v[136:137]
	v_lshlrev_b32_e32 v140, 16, v142
	v_and_b32_e32 v141, 0xffff0000, v142
	v_max_f32_e32 v140, v140, v140
	v_max_f32_e32 v141, v141, v141
	v_max_f32_e32 v140, 0x1e3ce508, v140
	v_max_f32_e32 v141, 0x1e3ce508, v141
	v_rcp_f32_e32 v140, v140
	v_rcp_f32_e32 v141, v141
	v_pk_mul_f32 v[78:79], v[78:79], v[136:137]
	v_lshlrev_b32_e32 v136, 16, v138
	v_and_b32_e32 v137, 0xffff0000, v138
	v_lshlrev_b32_e32 v138, 16, v143
	v_max_f32_e32 v138, v138, v138
	v_max_f32_e32 v138, 0x1e3ce508, v138
	v_pk_mul_f32 v[136:137], v[140:141], v[136:137]
	v_rcp_f32_e32 v140, v138
	v_and_b32_e32 v138, 0xffff0000, v143
	v_max_f32_e32 v138, v138, v138
	v_max_f32_e32 v138, 0x1e3ce508, v138
	v_rcp_f32_e32 v141, v138
	v_pk_mul_f32 v[72:73], v[72:73], v[136:137]
	v_lshlrev_b32_e32 v136, 16, v139
	v_and_b32_e32 v137, 0xffff0000, v139
	v_pk_mul_f32 v[136:137], v[140:141], v[136:137]
	v_lshlrev_b32_e32 v138, 16, v132
	v_and_b32_e32 v132, 0xffff0000, v132
	v_pk_mul_f32 v[74:75], v[74:75], v[136:137]
	v_lshlrev_b32_e32 v136, 16, v128
	v_and_b32_e32 v137, 0xffff0000, v128
	v_lshlrev_b32_e32 v128, 16, v133
	v_max_f32_e32 v132, v132, v132
	v_max_f32_e32 v128, v128, v128
	v_max_f32_e32 v132, 0x1e3ce508, v132
	v_max_f32_e32 v128, 0x1e3ce508, v128
	v_rcp_f32_e32 v139, v132
	v_rcp_f32_e32 v132, v128
	v_and_b32_e32 v128, 0xffff0000, v133
	v_max_f32_e32 v128, v128, v128
	v_max_f32_e32 v128, 0x1e3ce508, v128
	v_rcp_f32_e32 v133, v128
	v_lshlrev_b32_e32 v128, 16, v129
	v_and_b32_e32 v129, 0xffff0000, v129
	v_max_f32_e32 v138, v138, v138
	v_pk_mul_f32 v[128:129], v[132:133], v[128:129]
	v_lshlrev_b32_e32 v132, 16, v134
	v_and_b32_e32 v133, 0xffff0000, v134
	v_max_f32_e32 v132, v132, v132
	v_max_f32_e32 v133, v133, v133
	v_max_f32_e32 v132, 0x1e3ce508, v132
	v_max_f32_e32 v133, 0x1e3ce508, v133
	v_rcp_f32_e32 v132, v132
	v_rcp_f32_e32 v133, v133
	v_pk_mul_f32 v[70:71], v[70:71], v[128:129]
	v_lshlrev_b32_e32 v128, 16, v130
	v_and_b32_e32 v129, 0xffff0000, v130
	v_lshlrev_b32_e32 v130, 16, v135
	v_max_f32_e32 v130, v130, v130
	v_max_f32_e32 v130, 0x1e3ce508, v130
	v_pk_mul_f32 v[128:129], v[132:133], v[128:129]
	v_rcp_f32_e32 v132, v130
	v_and_b32_e32 v130, 0xffff0000, v135
	v_max_f32_e32 v130, v130, v130
	v_max_f32_e32 v199, 0x1e3ce508, v199
	v_max_f32_e32 v162, 0x1e3ce508, v162
	v_max_f32_e32 v154, 0x1e3ce508, v154
	v_max_f32_e32 v146, 0x1e3ce508, v146
	v_max_f32_e32 v138, 0x1e3ce508, v138
	v_max_f32_e32 v130, 0x1e3ce508, v130
	v_rcp_f32_e32 v202, v199
	v_rcp_f32_e32 v162, v162
	v_rcp_f32_e32 v154, v154
	v_rcp_f32_e32 v146, v146
	v_rcp_f32_e32 v138, v138
	v_rcp_f32_e32 v133, v130
	v_pk_mul_f32 v[64:65], v[64:65], v[128:129]
	v_lshlrev_b32_e32 v128, 16, v131
	v_and_b32_e32 v129, 0xffff0000, v131
	v_pk_mul_f32 v[226:227], v[226:227], v[228:229]
	v_pk_mul_f32 v[200:201], v[202:203], v[200:201]
	v_pk_mul_f32 v[160:161], v[162:163], v[160:161]
	v_pk_mul_f32 v[152:153], v[154:155], v[152:153]
	v_pk_mul_f32 v[144:145], v[146:147], v[144:145]
	v_pk_mul_f32 v[136:137], v[138:139], v[136:137]
	v_pk_mul_f32 v[128:129], v[132:133], v[128:129]
	v_pk_mul_f32 v[124:125], v[124:125], v[226:227]
	v_pk_mul_f32 v[100:101], v[100:101], v[200:201]
	v_pk_mul_f32 v[92:93], v[92:93], v[160:161]
	v_pk_mul_f32 v[84:85], v[84:85], v[152:153]
	v_pk_mul_f32 v[76:77], v[76:77], v[144:145]
	v_pk_mul_f32 v[68:69], v[68:69], v[136:137]
	v_pk_mul_f32 v[66:67], v[66:67], v[128:129]
	v_add_u32_e32 v128, 0x80, v198
	v_mad_i64_i32 v[128:129], s[30:31], v128, s49, v[188:189]
	v_lshl_add_u64 v[128:129], v[128:129], 0, s[28:29]
	v_lshl_add_u64 v[128:129], v[128:129], 0, v[190:191]
	v_lshl_add_u64 v[130:131], v[128:129], 0, s[18:19]
	global_load_dwordx4 v[200:203], v[128:129], off offset:3584
	global_load_dwordx4 v[206:209], v[128:129], off offset:3840
	global_load_dwordx4 v[210:213], v[130:131], off offset:2048
	global_load_dwordx4 v[214:217], v[130:131], off offset:2304
	v_add_u32_e32 v128, 0x90, v198
	v_mad_i64_i32 v[128:129], s[30:31], v128, s49, v[188:189]
	v_lshl_add_u64 v[128:129], v[128:129], 0, s[28:29]
	v_lshl_add_u64 v[128:129], v[128:129], 0, v[190:191]
	v_lshl_add_u64 v[130:131], v[128:129], 0, s[18:19]
	global_load_dwordx4 v[218:221], v[128:129], off offset:3584
	global_load_dwordx4 v[160:163], v[128:129], off offset:3840
	global_load_dwordx4 v[222:225], v[130:131], off offset:2048
	global_load_dwordx4 v[164:167], v[130:131], off offset:2304
	v_add_u32_e32 v128, 0xa0, v198
	v_mad_i64_i32 v[128:129], s[30:31], v128, s49, v[188:189]
	v_lshl_add_u64 v[128:129], v[128:129], 0, s[28:29]
	v_lshl_add_u64 v[128:129], v[128:129], 0, v[190:191]
	v_lshl_add_u64 v[130:131], v[128:129], 0, s[18:19]
	global_load_dwordx4 v[152:155], v[128:129], off offset:3584
	global_load_dwordx4 v[144:147], v[128:129], off offset:3840
	global_load_dwordx4 v[156:159], v[130:131], off offset:2048
	global_load_dwordx4 v[148:151], v[130:131], off offset:2304
	v_add_u32_e32 v128, 0xb0, v198
	v_mad_i64_i32 v[128:129], s[30:31], v128, s49, v[188:189]
	v_lshl_add_u64 v[128:129], v[128:129], 0, s[28:29]
	v_lshl_add_u64 v[128:129], v[128:129], 0, v[190:191]
	v_lshl_add_u64 v[132:133], v[128:129], 0, s[18:19]
	global_load_dwordx4 v[136:139], v[128:129], off offset:3584
	s_nop 0
	global_load_dwordx4 v[128:131], v[128:129], off offset:3840
	s_nop 0
	global_load_dwordx4 v[140:143], v[132:133], off offset:2048
	s_nop 0
	global_load_dwordx4 v[132:135], v[132:133], off offset:2304
	s_waitcnt vmcnt(13)
	v_lshlrev_b32_e32 v188, 16, v210
	v_and_b32_e32 v189, 0xffff0000, v210
	v_max_f32_e32 v188, v188, v188
	v_max_f32_e32 v189, v189, v189
	v_max_f32_e32 v188, 0x1e3ce508, v188
	v_max_f32_e32 v189, 0x1e3ce508, v189
	v_rcp_f32_e32 v188, v188
	v_rcp_f32_e32 v189, v189
	v_lshlrev_b32_e32 v190, 16, v200
	v_and_b32_e32 v191, 0xffff0000, v200
	v_pk_mul_f32 v[188:189], v[188:189], v[190:191]
	v_lshlrev_b32_e32 v190, 16, v211
	v_and_b32_e32 v191, 0xffff0000, v211
	v_max_f32_e32 v190, v190, v190
	v_max_f32_e32 v191, v191, v191
	v_max_f32_e32 v190, 0x1e3ce508, v190
	v_max_f32_e32 v191, 0x1e3ce508, v191
	v_rcp_f32_e32 v190, v190
	v_rcp_f32_e32 v191, v191
	v_pk_mul_f32 v[60:61], v[60:61], v[188:189]
	v_lshlrev_b32_e32 v188, 16, v201
	v_and_b32_e32 v189, 0xffff0000, v201
	v_pk_mul_f32 v[188:189], v[190:191], v[188:189]
	v_lshlrev_b32_e32 v190, 16, v212
	v_and_b32_e32 v191, 0xffff0000, v212
	v_max_f32_e32 v190, v190, v190
	v_max_f32_e32 v191, v191, v191
	v_max_f32_e32 v190, 0x1e3ce508, v190
	v_max_f32_e32 v191, 0x1e3ce508, v191
	v_rcp_f32_e32 v190, v190
	v_rcp_f32_e32 v191, v191
	v_pk_mul_f32 v[62:63], v[62:63], v[188:189]
	v_lshlrev_b32_e32 v188, 16, v202
	v_and_b32_e32 v189, 0xffff0000, v202
	v_pk_mul_f32 v[188:189], v[190:191], v[188:189]
	v_lshlrev_b32_e32 v190, 16, v213
	v_and_b32_e32 v191, 0xffff0000, v213
	v_max_f32_e32 v190, v190, v190
	v_max_f32_e32 v191, v191, v191
	v_max_f32_e32 v190, 0x1e3ce508, v190
	v_max_f32_e32 v191, 0x1e3ce508, v191
	v_rcp_f32_e32 v190, v190
	v_rcp_f32_e32 v191, v191
	v_pk_mul_f32 v[56:57], v[56:57], v[188:189]
	v_lshlrev_b32_e32 v188, 16, v203
	v_and_b32_e32 v189, 0xffff0000, v203
	v_pk_mul_f32 v[188:189], v[190:191], v[188:189]
	s_waitcnt vmcnt(12)
	v_lshlrev_b32_e32 v190, 16, v214
	v_and_b32_e32 v191, 0xffff0000, v214
	v_max_f32_e32 v190, v190, v190
	v_max_f32_e32 v191, v191, v191
	v_max_f32_e32 v190, 0x1e3ce508, v190
	v_max_f32_e32 v191, 0x1e3ce508, v191
	v_rcp_f32_e32 v190, v190
	v_rcp_f32_e32 v191, v191
	v_pk_mul_f32 v[58:59], v[58:59], v[188:189]
	v_lshlrev_b32_e32 v188, 16, v206
	v_and_b32_e32 v189, 0xffff0000, v206
	v_pk_mul_f32 v[188:189], v[190:191], v[188:189]
	v_lshlrev_b32_e32 v190, 16, v215
	v_and_b32_e32 v191, 0xffff0000, v215
	v_max_f32_e32 v190, v190, v190
	v_max_f32_e32 v191, v191, v191
	v_max_f32_e32 v190, 0x1e3ce508, v190
	v_max_f32_e32 v191, 0x1e3ce508, v191
	v_rcp_f32_e32 v190, v190
	v_rcp_f32_e32 v191, v191
	v_pk_mul_f32 v[52:53], v[52:53], v[188:189]
	v_lshlrev_b32_e32 v188, 16, v207
	v_and_b32_e32 v189, 0xffff0000, v207
	v_pk_mul_f32 v[188:189], v[190:191], v[188:189]
	v_lshlrev_b32_e32 v190, 16, v216
	v_and_b32_e32 v191, 0xffff0000, v216
	v_max_f32_e32 v190, v190, v190
	v_max_f32_e32 v191, v191, v191
	v_max_f32_e32 v190, 0x1e3ce508, v190
	v_max_f32_e32 v191, 0x1e3ce508, v191
	v_rcp_f32_e32 v190, v190
	v_rcp_f32_e32 v191, v191
	v_pk_mul_f32 v[54:55], v[54:55], v[188:189]
	v_lshlrev_b32_e32 v188, 16, v208
	v_and_b32_e32 v189, 0xffff0000, v208
	v_pk_mul_f32 v[188:189], v[190:191], v[188:189]
	v_lshlrev_b32_e32 v190, 16, v217
	v_and_b32_e32 v191, 0xffff0000, v217
	v_max_f32_e32 v190, v190, v190
	v_max_f32_e32 v191, v191, v191
	v_max_f32_e32 v190, 0x1e3ce508, v190
	v_max_f32_e32 v191, 0x1e3ce508, v191
	v_rcp_f32_e32 v190, v190
	v_rcp_f32_e32 v191, v191
	v_pk_mul_f32 v[48:49], v[48:49], v[188:189]
	v_lshlrev_b32_e32 v188, 16, v209
	v_and_b32_e32 v189, 0xffff0000, v209
	v_pk_mul_f32 v[188:189], v[190:191], v[188:189]
	s_waitcnt vmcnt(9)
	v_lshlrev_b32_e32 v190, 16, v222
	v_and_b32_e32 v191, 0xffff0000, v222
	v_max_f32_e32 v190, v190, v190
	v_max_f32_e32 v191, v191, v191
	v_max_f32_e32 v190, 0x1e3ce508, v190
	v_max_f32_e32 v191, 0x1e3ce508, v191
	v_rcp_f32_e32 v190, v190
	v_rcp_f32_e32 v191, v191
	v_pk_mul_f32 v[50:51], v[50:51], v[188:189]
	v_lshlrev_b32_e32 v188, 16, v218
	v_and_b32_e32 v189, 0xffff0000, v218
	v_pk_mul_f32 v[188:189], v[190:191], v[188:189]
	v_lshlrev_b32_e32 v190, 16, v223
	v_and_b32_e32 v191, 0xffff0000, v223
	v_max_f32_e32 v190, v190, v190
	v_max_f32_e32 v191, v191, v191
	v_max_f32_e32 v190, 0x1e3ce508, v190
	v_max_f32_e32 v191, 0x1e3ce508, v191
	v_rcp_f32_e32 v190, v190
	v_rcp_f32_e32 v191, v191
	v_pk_mul_f32 v[44:45], v[44:45], v[188:189]
	v_lshlrev_b32_e32 v188, 16, v219
	v_and_b32_e32 v189, 0xffff0000, v219
	v_pk_mul_f32 v[188:189], v[190:191], v[188:189]
	v_lshlrev_b32_e32 v190, 16, v224
	v_and_b32_e32 v191, 0xffff0000, v224
	v_max_f32_e32 v190, v190, v190
	v_max_f32_e32 v191, v191, v191
	v_max_f32_e32 v190, 0x1e3ce508, v190
	v_max_f32_e32 v191, 0x1e3ce508, v191
	v_rcp_f32_e32 v190, v190
	v_rcp_f32_e32 v191, v191
	v_pk_mul_f32 v[46:47], v[46:47], v[188:189]
	v_lshlrev_b32_e32 v188, 16, v220
	v_and_b32_e32 v189, 0xffff0000, v220
	v_pk_mul_f32 v[188:189], v[190:191], v[188:189]
	v_lshlrev_b32_e32 v190, 16, v225
	v_and_b32_e32 v191, 0xffff0000, v225
	v_max_f32_e32 v190, v190, v190
	v_max_f32_e32 v191, v191, v191
	v_max_f32_e32 v190, 0x1e3ce508, v190
	v_max_f32_e32 v191, 0x1e3ce508, v191
	v_rcp_f32_e32 v190, v190
	v_rcp_f32_e32 v191, v191
	v_pk_mul_f32 v[40:41], v[40:41], v[188:189]
	v_lshlrev_b32_e32 v188, 16, v221
	v_and_b32_e32 v189, 0xffff0000, v221
	v_pk_mul_f32 v[188:189], v[190:191], v[188:189]
	s_waitcnt vmcnt(8)
	v_lshlrev_b32_e32 v190, 16, v164
	v_and_b32_e32 v164, 0xffff0000, v164
	v_pk_mul_f32 v[42:43], v[42:43], v[188:189]
	v_lshlrev_b32_e32 v188, 16, v160
	v_and_b32_e32 v189, 0xffff0000, v160
	v_lshlrev_b32_e32 v160, 16, v165
	v_max_f32_e32 v164, v164, v164
	v_max_f32_e32 v160, v160, v160
	v_max_f32_e32 v164, 0x1e3ce508, v164
	v_max_f32_e32 v160, 0x1e3ce508, v160
	v_rcp_f32_e32 v191, v164
	v_rcp_f32_e32 v164, v160
	v_and_b32_e32 v160, 0xffff0000, v165
	v_max_f32_e32 v160, v160, v160
	v_max_f32_e32 v160, 0x1e3ce508, v160
	v_rcp_f32_e32 v165, v160
	v_lshlrev_b32_e32 v160, 16, v161
	v_and_b32_e32 v161, 0xffff0000, v161
	v_max_f32_e32 v190, v190, v190
	v_pk_mul_f32 v[160:161], v[164:165], v[160:161]
	v_lshlrev_b32_e32 v164, 16, v166
	v_and_b32_e32 v165, 0xffff0000, v166
	v_max_f32_e32 v164, v164, v164
	v_max_f32_e32 v165, v165, v165
	v_max_f32_e32 v164, 0x1e3ce508, v164
	v_max_f32_e32 v165, 0x1e3ce508, v165
	v_rcp_f32_e32 v164, v164
	v_rcp_f32_e32 v165, v165
	v_pk_mul_f32 v[38:39], v[38:39], v[160:161]
	v_lshlrev_b32_e32 v160, 16, v162
	v_and_b32_e32 v161, 0xffff0000, v162
	v_lshlrev_b32_e32 v162, 16, v167
	v_max_f32_e32 v162, v162, v162
	v_max_f32_e32 v162, 0x1e3ce508, v162
	v_pk_mul_f32 v[160:161], v[164:165], v[160:161]
	v_rcp_f32_e32 v164, v162
	v_and_b32_e32 v162, 0xffff0000, v167
	v_max_f32_e32 v162, v162, v162
	v_max_f32_e32 v162, 0x1e3ce508, v162
	v_rcp_f32_e32 v165, v162
	v_pk_mul_f32 v[32:33], v[32:33], v[160:161]
	v_lshlrev_b32_e32 v160, 16, v163
	v_and_b32_e32 v161, 0xffff0000, v163
	v_pk_mul_f32 v[160:161], v[164:165], v[160:161]
	s_waitcnt vmcnt(5)
	v_lshlrev_b32_e32 v162, 16, v156
	v_and_b32_e32 v156, 0xffff0000, v156
	v_pk_mul_f32 v[34:35], v[34:35], v[160:161]
	v_lshlrev_b32_e32 v160, 16, v152
	v_and_b32_e32 v161, 0xffff0000, v152
	v_lshlrev_b32_e32 v152, 16, v157
	v_max_f32_e32 v156, v156, v156
	v_max_f32_e32 v152, v152, v152
	v_max_f32_e32 v156, 0x1e3ce508, v156
	v_max_f32_e32 v152, 0x1e3ce508, v152
	v_rcp_f32_e32 v163, v156
	v_rcp_f32_e32 v156, v152
	v_and_b32_e32 v152, 0xffff0000, v157
	v_max_f32_e32 v152, v152, v152
	v_max_f32_e32 v152, 0x1e3ce508, v152
	v_rcp_f32_e32 v157, v152
	v_lshlrev_b32_e32 v152, 16, v153
	v_and_b32_e32 v153, 0xffff0000, v153
	v_max_f32_e32 v162, v162, v162
	v_pk_mul_f32 v[152:153], v[156:157], v[152:153]
	v_lshlrev_b32_e32 v156, 16, v158
	v_and_b32_e32 v157, 0xffff0000, v158
	v_max_f32_e32 v156, v156, v156
	v_max_f32_e32 v157, v157, v157
	v_max_f32_e32 v156, 0x1e3ce508, v156
	v_max_f32_e32 v157, 0x1e3ce508, v157
	v_rcp_f32_e32 v156, v156
	v_rcp_f32_e32 v157, v157
	v_pk_mul_f32 v[30:31], v[30:31], v[152:153]
	v_lshlrev_b32_e32 v152, 16, v154
	v_and_b32_e32 v153, 0xffff0000, v154
	v_lshlrev_b32_e32 v154, 16, v159
	v_max_f32_e32 v154, v154, v154
	v_max_f32_e32 v154, 0x1e3ce508, v154
	v_pk_mul_f32 v[152:153], v[156:157], v[152:153]
	v_rcp_f32_e32 v156, v154
	v_and_b32_e32 v154, 0xffff0000, v159
	v_max_f32_e32 v154, v154, v154
	v_max_f32_e32 v154, 0x1e3ce508, v154
	v_rcp_f32_e32 v157, v154
	v_pk_mul_f32 v[24:25], v[24:25], v[152:153]
	v_lshlrev_b32_e32 v152, 16, v155
	v_and_b32_e32 v153, 0xffff0000, v155
	v_pk_mul_f32 v[152:153], v[156:157], v[152:153]
	s_waitcnt vmcnt(4)
	v_lshlrev_b32_e32 v154, 16, v148
	v_and_b32_e32 v148, 0xffff0000, v148
	v_pk_mul_f32 v[26:27], v[26:27], v[152:153]
	v_lshlrev_b32_e32 v152, 16, v144
	v_and_b32_e32 v153, 0xffff0000, v144
	v_lshlrev_b32_e32 v144, 16, v149
	v_max_f32_e32 v148, v148, v148
	v_max_f32_e32 v144, v144, v144
	v_max_f32_e32 v148, 0x1e3ce508, v148
	v_max_f32_e32 v144, 0x1e3ce508, v144
	v_rcp_f32_e32 v155, v148
	v_rcp_f32_e32 v148, v144
	v_and_b32_e32 v144, 0xffff0000, v149
	v_max_f32_e32 v144, v144, v144
	v_max_f32_e32 v144, 0x1e3ce508, v144
	v_rcp_f32_e32 v149, v144
	v_lshlrev_b32_e32 v144, 16, v145
	v_and_b32_e32 v145, 0xffff0000, v145
	v_max_f32_e32 v154, v154, v154
	v_pk_mul_f32 v[144:145], v[148:149], v[144:145]
	v_lshlrev_b32_e32 v148, 16, v150
	v_and_b32_e32 v149, 0xffff0000, v150
	v_max_f32_e32 v148, v148, v148
	v_max_f32_e32 v149, v149, v149
	v_max_f32_e32 v148, 0x1e3ce508, v148
	v_max_f32_e32 v149, 0x1e3ce508, v149
	v_rcp_f32_e32 v148, v148
	v_rcp_f32_e32 v149, v149
	v_pk_mul_f32 v[22:23], v[22:23], v[144:145]
	v_lshlrev_b32_e32 v144, 16, v146
	v_and_b32_e32 v145, 0xffff0000, v146
	v_lshlrev_b32_e32 v146, 16, v151
	v_max_f32_e32 v146, v146, v146
	v_max_f32_e32 v146, 0x1e3ce508, v146
	v_pk_mul_f32 v[144:145], v[148:149], v[144:145]
	v_rcp_f32_e32 v148, v146
	v_and_b32_e32 v146, 0xffff0000, v151
	v_max_f32_e32 v146, v146, v146
	v_max_f32_e32 v146, 0x1e3ce508, v146
	v_rcp_f32_e32 v149, v146
	v_pk_mul_f32 v[16:17], v[16:17], v[144:145]
	v_lshlrev_b32_e32 v144, 16, v147
	v_and_b32_e32 v145, 0xffff0000, v147
	v_pk_mul_f32 v[144:145], v[148:149], v[144:145]
	s_waitcnt vmcnt(1)
	v_lshlrev_b32_e32 v146, 16, v140
	v_and_b32_e32 v140, 0xffff0000, v140
	v_pk_mul_f32 v[18:19], v[18:19], v[144:145]
	v_lshlrev_b32_e32 v144, 16, v136
	v_and_b32_e32 v145, 0xffff0000, v136
	v_lshlrev_b32_e32 v136, 16, v141
	v_max_f32_e32 v140, v140, v140
	v_max_f32_e32 v136, v136, v136
	v_max_f32_e32 v140, 0x1e3ce508, v140
	v_max_f32_e32 v136, 0x1e3ce508, v136
	v_rcp_f32_e32 v147, v140
	v_rcp_f32_e32 v140, v136
	v_and_b32_e32 v136, 0xffff0000, v141
	v_max_f32_e32 v136, v136, v136
	v_max_f32_e32 v136, 0x1e3ce508, v136
	v_rcp_f32_e32 v141, v136
	v_lshlrev_b32_e32 v136, 16, v137
	v_and_b32_e32 v137, 0xffff0000, v137
	v_max_f32_e32 v146, v146, v146
	v_pk_mul_f32 v[136:137], v[140:141], v[136:137]
	v_lshlrev_b32_e32 v140, 16, v142
	v_and_b32_e32 v141, 0xffff0000, v142
	v_max_f32_e32 v140, v140, v140
	v_max_f32_e32 v141, v141, v141
	v_max_f32_e32 v140, 0x1e3ce508, v140
	v_max_f32_e32 v141, 0x1e3ce508, v141
	v_rcp_f32_e32 v140, v140
	v_rcp_f32_e32 v141, v141
	v_pk_mul_f32 v[14:15], v[14:15], v[136:137]
	v_lshlrev_b32_e32 v136, 16, v138
	v_and_b32_e32 v137, 0xffff0000, v138
	v_lshlrev_b32_e32 v138, 16, v143
	v_max_f32_e32 v138, v138, v138
	v_max_f32_e32 v138, 0x1e3ce508, v138
	v_pk_mul_f32 v[136:137], v[140:141], v[136:137]
	v_rcp_f32_e32 v140, v138
	v_and_b32_e32 v138, 0xffff0000, v143
	v_max_f32_e32 v138, v138, v138
	v_max_f32_e32 v138, 0x1e3ce508, v138
	v_rcp_f32_e32 v141, v138
	v_pk_mul_f32 v[8:9], v[8:9], v[136:137]
	v_lshlrev_b32_e32 v136, 16, v139
	v_and_b32_e32 v137, 0xffff0000, v139
	v_pk_mul_f32 v[136:137], v[140:141], v[136:137]
	s_waitcnt vmcnt(0)
	v_lshlrev_b32_e32 v138, 16, v132
	v_and_b32_e32 v132, 0xffff0000, v132
	v_pk_mul_f32 v[10:11], v[10:11], v[136:137]
	v_lshlrev_b32_e32 v136, 16, v128
	v_and_b32_e32 v137, 0xffff0000, v128
	v_lshlrev_b32_e32 v128, 16, v133
	v_max_f32_e32 v132, v132, v132
	v_max_f32_e32 v128, v128, v128
	v_max_f32_e32 v132, 0x1e3ce508, v132
	v_max_f32_e32 v128, 0x1e3ce508, v128
	v_rcp_f32_e32 v139, v132
	v_rcp_f32_e32 v132, v128
	v_and_b32_e32 v128, 0xffff0000, v133
	v_max_f32_e32 v128, v128, v128
	v_max_f32_e32 v128, 0x1e3ce508, v128
	v_rcp_f32_e32 v133, v128
	v_lshlrev_b32_e32 v128, 16, v129
	v_and_b32_e32 v129, 0xffff0000, v129
	v_max_f32_e32 v138, v138, v138
	v_pk_mul_f32 v[128:129], v[132:133], v[128:129]
	v_lshlrev_b32_e32 v132, 16, v134
	v_and_b32_e32 v133, 0xffff0000, v134
	v_max_f32_e32 v132, v132, v132
	v_max_f32_e32 v133, v133, v133
	v_max_f32_e32 v132, 0x1e3ce508, v132
	v_max_f32_e32 v133, 0x1e3ce508, v133
	v_rcp_f32_e32 v132, v132
	v_rcp_f32_e32 v133, v133
	v_pk_mul_f32 v[6:7], v[6:7], v[128:129]
	v_lshlrev_b32_e32 v128, 16, v130
	v_and_b32_e32 v129, 0xffff0000, v130
	v_lshlrev_b32_e32 v130, 16, v135
	v_max_f32_e32 v130, v130, v130
	v_max_f32_e32 v130, 0x1e3ce508, v130
	v_pk_mul_f32 v[128:129], v[132:133], v[128:129]
	v_rcp_f32_e32 v132, v130
	v_and_b32_e32 v130, 0xffff0000, v135
	v_max_f32_e32 v130, v130, v130
	v_max_f32_e32 v190, 0x1e3ce508, v190
	v_max_f32_e32 v162, 0x1e3ce508, v162
	v_max_f32_e32 v154, 0x1e3ce508, v154
	v_max_f32_e32 v146, 0x1e3ce508, v146
	v_max_f32_e32 v138, 0x1e3ce508, v138
	v_max_f32_e32 v130, 0x1e3ce508, v130
	v_rcp_f32_e32 v190, v190
	v_rcp_f32_e32 v162, v162
	v_rcp_f32_e32 v154, v154
	v_rcp_f32_e32 v146, v146
	v_rcp_f32_e32 v138, v138
	v_rcp_f32_e32 v133, v130
	v_pk_mul_f32 v[0:1], v[0:1], v[128:129]
	v_lshlrev_b32_e32 v128, 16, v131
	v_and_b32_e32 v129, 0xffff0000, v131
	v_pk_mul_f32 v[188:189], v[190:191], v[188:189]
	v_pk_mul_f32 v[160:161], v[162:163], v[160:161]
	v_pk_mul_f32 v[152:153], v[154:155], v[152:153]
	v_pk_mul_f32 v[144:145], v[146:147], v[144:145]
	v_pk_mul_f32 v[136:137], v[138:139], v[136:137]
	v_pk_mul_f32 v[128:129], v[132:133], v[128:129]
	v_pk_mul_f32 v[36:37], v[36:37], v[188:189]
	v_pk_mul_f32 v[28:29], v[28:29], v[160:161]
	v_pk_mul_f32 v[20:21], v[20:21], v[152:153]
	v_pk_mul_f32 v[12:13], v[12:13], v[144:145]
	v_pk_mul_f32 v[4:5], v[4:5], v[136:137]
	v_pk_mul_f32 v[2:3], v[2:3], v[128:129]
	s_andn2_b64 vcc, exec, s[8:9]
	s_cbranch_vccnz .Lhk_b_2
	s_barrier
.Lhk_b_2:
	s_branch .LBB0_2155
.LBB0_2162:
	s_and_b64 vcc, exec, s[16:17]
	s_cbranch_vccz .LBB0_2164
	s_barrier
